# norm fast path: XCD-aware row blocks (each workgroup normalises rows its own XCD just wrote, L2 locality)
# speedup vs baseline: 1.0106x; 1.0012x over previous
.LBB0_221:
	s_andn2_b64 vcc, exec, s[4:5]
	s_cbranch_vccnz .LBB0_289
	v_readlane_b32 s8, v253, 2
	s_mov_b64 s[4:5], s[96:97]
	s_mov_b64 s[36:37], s[96:97]
	s_mov_b64 s[20:21], s[96:97]
	v_mov_b32_e32 v2, v0
	v_readlane_b32 s9, v253, 3
	s_load_dword s6, s[8:9], 0x0
	v_readfirstlane_b32 s7, v2
	s_ashr_i32 s10, s7, 6
	v_readlane_b32 s7, v254, 16
	s_add_i32 s7, s10, s7
	s_cmpk_gt_i32 s7, 0x43ff
	s_cbranch_scc1 .LBB0_235
	s_load_dwordx2 s[8:9], s[36:37], 0xb8
	s_waitcnt lgkmcnt(0)
	s_mul_i32 s52, s80, 0x5000
	s_load_dwordx2 s[20:21], s[20:21], 0xb8
	s_lshl_b64 s[36:37], s[52:53], 2
	s_mul_i32 s52, s80, 0xf000
	s_waitcnt lgkmcnt(0)
	s_add_u32 s8, s8, s36
	s_addc_u32 s9, s9, s37
	s_add_u32 s8, s8, 0x195d4000
	s_addc_u32 s9, s9, 0
	s_lshl_b64 s[36:37], s[52:53], 2
	s_load_dwordx2 s[38:39], s[4:5], 0xb8
	s_add_u32 s11, s20, s36
	s_addc_u32 s12, s21, s37
	s_add_u32 s54, s11, 0x194e0000
	v_and_b32_e32 v3, 63, v2
	s_addc_u32 s55, s12, 0
	v_lshlrev_b32_e32 v98, 5, v3
	s_cmp_lg_u32 s80, 0
	s_waitcnt lgkmcnt(0)
	v_lshl_add_u64 v[4:5], s[38:39], 0, v[98:99]
	s_mov_b64 s[12:13], 0x3bce8000
	s_cselect_b64 s[20:21], -1, 0
	s_lshl_b32 s36, s6, 3
	v_lshl_add_u64 v[34:35], v[4:5], 0, s[12:13]
	s_ashr_i32 s11, s10, 31
	v_readlane_b32 s12, v254, 16
	s_add_u32 s10, s12, s10
	v_readlane_b32 s12, v254, 58
	s_addc_u32 s11, s12, s11
	s_lshl_b64 s[40:41], s[10:11], 12
	s_add_u32 s38, s38, s40
	v_lshlrev_b32_e32 v4, 3, v3
	v_lshlrev_b32_e32 v98, 4, v3
	s_addc_u32 s39, s39, s41
	v_lshlrev_b32_e32 v2, 1, v3
	v_or_b32_e32 v6, 0x400, v4
	v_or_b32_e32 v8, 0x600, v4
	v_lshl_add_u64 v[10:11], s[38:39], 0, v[98:99]
	s_mov_b64 s[12:13], 0x1da24c00
	s_ashr_i32 s37, s36, 31
	v_lshl_add_u64 v[36:37], v[10:11], 0, s[12:13]
	s_lshl_b64 s[38:39], s[36:37], 12
	s_lshl_b64 s[42:43], s[10:11], 13
	s_lshl_b64 s[44:45], s[36:37], 13
	v_cndmask_b32_e64 v56, 0, 1, s[20:21]
	v_lshlrev_b32_e32 v98, 4, v2
	s_xor_b64 s[46:47], s[20:21], -1
	v_lshlrev_b32_e32 v57, 2, v4
	v_lshlrev_b32_e32 v58, 2, v6
	v_lshlrev_b32_e32 v59, 2, v8
	s_mov_b32 s101, 0
	s_cmp_lg_u32 s6, 0x100
	s_cbranch_scc1 .Lnf1_skip
	s_cmp_eq_u32 s80, 0
	s_cbranch_scc1 .Lnf1_skip
	s_mov_b32 s101, 1
	s_load_dwordx2 s[40:41], s[4:5], 0xb8
	v_and_b32_e32 v38, 63, v0
	v_lshlrev_b32_e32 v39, 4, v38
	v_lshlrev_b32_e32 v40, 5, v38
	s_lshr_b32 s20, s7, 3
	s_and_b32 s21, s20, 7
	s_lshl_b32 s21, s21, 5
	s_lshr_b32 s20, s20, 3
	s_or_b32 s20, s20, s21
	s_lshl_b32 s20, s20, 3
	s_and_b32 s21, s7, 7
	s_or_b32 s49, s20, s21
	s_lshl_b32 s10, s49, 15
	s_lshr_b32 s48, s49, 9
	s_lshl_b32 s20, s48, 13
	s_mul_i32 s49, s48, 0xc000
	s_waitcnt lgkmcnt(0)
	s_add_u32 s10, s40, s10
	s_addc_u32 s11, s41, 0
	s_add_u32 s10, s10, 0x19624000
	s_addc_u32 s11, s11, 0
	s_add_u32 s40, s8, s20
	s_addc_u32 s41, s9, 0
	s_add_u32 s48, s54, s49
	s_addc_u32 s49, s55, 0
	s_add_u32 s20, s10, 0x4400000
	s_addc_u32 s21, s11, 0
	global_load_dwordx4 v[100:103], v39, s[10:11]
	global_load_dwordx4 v[104:107], v39, s[10:11] offset:1024
	global_load_dwordx4 v[108:111], v39, s[10:11] offset:2048
	global_load_dwordx4 v[112:115], v39, s[10:11] offset:3072
	s_add_u32 s10, s10, 0x1000
	s_addc_u32 s11, s11, 0
	global_load_dwordx4 v[2:5], v40, s[40:41]
	global_load_dwordx4 v[6:9], v40, s[40:41] offset:16
	global_load_dwordx4 v[10:13], v40, s[40:41] offset:2048
	global_load_dwordx4 v[14:17], v40, s[40:41] offset:2064
	s_add_u32 s40, s40, 0x1000
	s_addc_u32 s41, s41, 0
	global_load_dwordx4 v[18:21], v40, s[40:41]
	global_load_dwordx4 v[22:25], v40, s[40:41] offset:16
	global_load_dwordx4 v[26:29], v40, s[40:41] offset:2048
	global_load_dwordx4 v[30:33], v40, s[40:41] offset:2064
	global_load_dwordx4 v[164:167], v40, s[48:49]
	global_load_dwordx4 v[168:171], v40, s[48:49] offset:16
	global_load_dwordx4 v[172:175], v40, s[48:49] offset:2048
	global_load_dwordx4 v[176:179], v40, s[48:49] offset:2064
	s_add_u32 s48, s48, 0x1000
	s_addc_u32 s49, s49, 0
	global_load_dwordx4 v[180:183], v40, s[48:49]
	global_load_dwordx4 v[184:187], v40, s[48:49] offset:16
	global_load_dwordx4 v[188:191], v40, s[48:49] offset:2048
	global_load_dwordx4 v[192:195], v40, s[48:49] offset:2064
	global_load_dwordx4 v[116:119], v39, s[10:11]
	global_load_dwordx4 v[120:123], v39, s[10:11] offset:1024
	global_load_dwordx4 v[124:127], v39, s[10:11] offset:2048
	global_load_dwordx4 v[128:131], v39, s[10:11] offset:3072
	s_add_u32 s10, s10, 0x1000
	s_addc_u32 s11, s11, 0
	global_load_dwordx4 v[132:135], v39, s[10:11]
	global_load_dwordx4 v[136:139], v39, s[10:11] offset:1024
	global_load_dwordx4 v[140:143], v39, s[10:11] offset:2048
	global_load_dwordx4 v[144:147], v39, s[10:11] offset:3072
	s_add_u32 s10, s10, 0x1000
	s_addc_u32 s11, s11, 0
	global_load_dwordx4 v[148:151], v39, s[10:11]
	global_load_dwordx4 v[152:155], v39, s[10:11] offset:1024
	global_load_dwordx4 v[156:159], v39, s[10:11] offset:2048
	global_load_dwordx4 v[160:163], v39, s[10:11] offset:3072
	s_add_u32 s10, s10, 0x1000
	s_addc_u32 s11, s11, 0
	v_mov_b32_e32 v47, 0x3a000000
	s_waitcnt vmcnt(28)
	v_lshlrev_b32_e32 v60, 16, v100
	v_and_b32_e32 v61, 0xffff0000, v100
	v_pk_mul_f32 v[42:43], v[60:61], v[60:61]
	v_lshlrev_b32_e32 v62, 16, v101
	v_and_b32_e32 v63, 0xffff0000, v101
	v_pk_fma_f32 v[42:43], v[62:63], v[62:63], v[42:43]
	v_lshlrev_b32_e32 v64, 16, v102
	v_and_b32_e32 v65, 0xffff0000, v102
	v_pk_fma_f32 v[42:43], v[64:65], v[64:65], v[42:43]
	v_lshlrev_b32_e32 v66, 16, v103
	v_and_b32_e32 v67, 0xffff0000, v103
	v_pk_fma_f32 v[42:43], v[66:67], v[66:67], v[42:43]
	v_lshlrev_b32_e32 v60, 16, v104
	v_and_b32_e32 v61, 0xffff0000, v104
	v_pk_fma_f32 v[42:43], v[60:61], v[60:61], v[42:43]
	v_lshlrev_b32_e32 v62, 16, v105
	v_and_b32_e32 v63, 0xffff0000, v105
	v_pk_fma_f32 v[42:43], v[62:63], v[62:63], v[42:43]
	v_lshlrev_b32_e32 v64, 16, v106
	v_and_b32_e32 v65, 0xffff0000, v106
	v_pk_fma_f32 v[42:43], v[64:65], v[64:65], v[42:43]
	v_lshlrev_b32_e32 v66, 16, v107
	v_and_b32_e32 v67, 0xffff0000, v107
	v_pk_fma_f32 v[42:43], v[66:67], v[66:67], v[42:43]
	v_lshlrev_b32_e32 v60, 16, v108
	v_and_b32_e32 v61, 0xffff0000, v108
	v_pk_fma_f32 v[42:43], v[60:61], v[60:61], v[42:43]
	v_lshlrev_b32_e32 v62, 16, v109
	v_and_b32_e32 v63, 0xffff0000, v109
	v_pk_fma_f32 v[42:43], v[62:63], v[62:63], v[42:43]
	v_lshlrev_b32_e32 v64, 16, v110
	v_and_b32_e32 v65, 0xffff0000, v110
	v_pk_fma_f32 v[42:43], v[64:65], v[64:65], v[42:43]
	v_lshlrev_b32_e32 v66, 16, v111
	v_and_b32_e32 v67, 0xffff0000, v111
	v_pk_fma_f32 v[42:43], v[66:67], v[66:67], v[42:43]
	v_lshlrev_b32_e32 v60, 16, v112
	v_and_b32_e32 v61, 0xffff0000, v112
	v_pk_fma_f32 v[42:43], v[60:61], v[60:61], v[42:43]
	v_lshlrev_b32_e32 v62, 16, v113
	v_and_b32_e32 v63, 0xffff0000, v113
	v_pk_fma_f32 v[42:43], v[62:63], v[62:63], v[42:43]
	v_lshlrev_b32_e32 v64, 16, v114
	v_and_b32_e32 v65, 0xffff0000, v114
	v_pk_fma_f32 v[42:43], v[64:65], v[64:65], v[42:43]
	v_lshlrev_b32_e32 v66, 16, v115
	v_and_b32_e32 v67, 0xffff0000, v115
	v_pk_fma_f32 v[42:43], v[66:67], v[66:67], v[42:43]
	v_add_f32_e32 v42, v42, v43
	s_nop 1
	v_add_f32_dpp v42, v42, v42 quad_perm:[1,0,3,2] row_mask:0xf bank_mask:0xf
	s_nop 1
	v_add_f32_dpp v42, v42, v42 quad_perm:[2,3,0,1] row_mask:0xf bank_mask:0xf
	s_nop 1
	v_add_f32_dpp v42, v42, v42 row_half_mirror row_mask:0xf bank_mask:0xf
	s_nop 1
	v_add_f32_dpp v42, v42, v42 row_mirror row_mask:0xf bank_mask:0xf
	s_nop 1
	v_add_f32_dpp v42, v42, v42 row_bcast:15 row_mask:0xa bank_mask:0xf
	s_nop 1
	v_add_f32_dpp v42, v42, v42 row_bcast:31 row_mask:0xc bank_mask:0xf
	s_nop 1
	v_readlane_b32 s100, v42, 63
	s_nop 3
	v_mov_b32_e32 v44, s100
	v_fma_f32 v44, v44, v47, v224
	v_rsq_f32_e32 v45, v44
	s_nop 0
	v_mul_f32_e32 v46, v44, v45
	v_mul_f32_e32 v46, v46, v45
	v_fmaak_f32 v46, -0.5, v46, 0x3fc00000
	v_mul_f32_e32 v44, v45, v46
	v_mov_b32_e32 v45, v44
	s_waitcnt vmcnt(12)
	v_lshlrev_b32_e32 v60, 16, v100
	v_and_b32_e32 v61, 0xffff0000, v100
	v_pk_mul_f32 v[60:61], v[60:61], v[44:45]
	v_pk_fma_f32 v[60:61], v[60:61], v[2:3], v[164:165]
	v_cvt_pk_bf16_f32 v100, v60, v61
	v_lshlrev_b32_e32 v62, 16, v101
	v_and_b32_e32 v63, 0xffff0000, v101
	v_pk_mul_f32 v[62:63], v[62:63], v[44:45]
	v_pk_fma_f32 v[62:63], v[62:63], v[4:5], v[166:167]
	v_cvt_pk_bf16_f32 v101, v62, v63
	v_lshlrev_b32_e32 v64, 16, v102
	v_and_b32_e32 v65, 0xffff0000, v102
	v_pk_mul_f32 v[64:65], v[64:65], v[44:45]
	v_pk_fma_f32 v[64:65], v[64:65], v[6:7], v[168:169]
	v_cvt_pk_bf16_f32 v102, v64, v65
	v_lshlrev_b32_e32 v66, 16, v103
	v_and_b32_e32 v67, 0xffff0000, v103
	v_pk_mul_f32 v[66:67], v[66:67], v[44:45]
	v_pk_fma_f32 v[66:67], v[66:67], v[8:9], v[170:171]
	v_cvt_pk_bf16_f32 v103, v66, v67
	v_lshlrev_b32_e32 v60, 16, v104
	v_and_b32_e32 v61, 0xffff0000, v104
	v_pk_mul_f32 v[60:61], v[60:61], v[44:45]
	v_pk_fma_f32 v[60:61], v[60:61], v[10:11], v[172:173]
	v_cvt_pk_bf16_f32 v104, v60, v61
	v_lshlrev_b32_e32 v62, 16, v105
	v_and_b32_e32 v63, 0xffff0000, v105
	v_pk_mul_f32 v[62:63], v[62:63], v[44:45]
	v_pk_fma_f32 v[62:63], v[62:63], v[12:13], v[174:175]
	v_cvt_pk_bf16_f32 v105, v62, v63
	v_lshlrev_b32_e32 v64, 16, v106
	v_and_b32_e32 v65, 0xffff0000, v106
	v_pk_mul_f32 v[64:65], v[64:65], v[44:45]
	v_pk_fma_f32 v[64:65], v[64:65], v[14:15], v[176:177]
	v_cvt_pk_bf16_f32 v106, v64, v65
	v_lshlrev_b32_e32 v66, 16, v107
	v_and_b32_e32 v67, 0xffff0000, v107
	v_pk_mul_f32 v[66:67], v[66:67], v[44:45]
	v_pk_fma_f32 v[66:67], v[66:67], v[16:17], v[178:179]
	v_cvt_pk_bf16_f32 v107, v66, v67
	v_lshlrev_b32_e32 v60, 16, v108
	v_and_b32_e32 v61, 0xffff0000, v108
	v_pk_mul_f32 v[60:61], v[60:61], v[44:45]
	v_pk_fma_f32 v[60:61], v[60:61], v[18:19], v[180:181]
	v_cvt_pk_bf16_f32 v108, v60, v61
	v_lshlrev_b32_e32 v62, 16, v109
	v_and_b32_e32 v63, 0xffff0000, v109
	v_pk_mul_f32 v[62:63], v[62:63], v[44:45]
	v_pk_fma_f32 v[62:63], v[62:63], v[20:21], v[182:183]
	v_cvt_pk_bf16_f32 v109, v62, v63
	v_lshlrev_b32_e32 v64, 16, v110
	v_and_b32_e32 v65, 0xffff0000, v110
	v_pk_mul_f32 v[64:65], v[64:65], v[44:45]
	v_pk_fma_f32 v[64:65], v[64:65], v[22:23], v[184:185]
	v_cvt_pk_bf16_f32 v110, v64, v65
	v_lshlrev_b32_e32 v66, 16, v111
	v_and_b32_e32 v67, 0xffff0000, v111
	v_pk_mul_f32 v[66:67], v[66:67], v[44:45]
	v_pk_fma_f32 v[66:67], v[66:67], v[24:25], v[186:187]
	v_cvt_pk_bf16_f32 v111, v66, v67
	v_lshlrev_b32_e32 v60, 16, v112
	v_and_b32_e32 v61, 0xffff0000, v112
	v_pk_mul_f32 v[60:61], v[60:61], v[44:45]
	v_pk_fma_f32 v[60:61], v[60:61], v[26:27], v[188:189]
	v_cvt_pk_bf16_f32 v112, v60, v61
	v_lshlrev_b32_e32 v62, 16, v113
	v_and_b32_e32 v63, 0xffff0000, v113
	v_pk_mul_f32 v[62:63], v[62:63], v[44:45]
	v_pk_fma_f32 v[62:63], v[62:63], v[28:29], v[190:191]
	v_cvt_pk_bf16_f32 v113, v62, v63
	v_lshlrev_b32_e32 v64, 16, v114
	v_and_b32_e32 v65, 0xffff0000, v114
	v_pk_mul_f32 v[64:65], v[64:65], v[44:45]
	v_pk_fma_f32 v[64:65], v[64:65], v[30:31], v[192:193]
	v_cvt_pk_bf16_f32 v114, v64, v65
	v_lshlrev_b32_e32 v66, 16, v115
	v_and_b32_e32 v67, 0xffff0000, v115
	v_pk_mul_f32 v[66:67], v[66:67], v[44:45]
	v_pk_fma_f32 v[66:67], v[66:67], v[32:33], v[194:195]
	v_cvt_pk_bf16_f32 v115, v66, v67
	global_store_dwordx4 v39, v[100:103], s[20:21]
	global_store_dwordx4 v39, v[104:107], s[20:21] offset:1024
	global_store_dwordx4 v39, v[108:111], s[20:21] offset:2048
	global_store_dwordx4 v39, v[112:115], s[20:21] offset:3072
	s_add_u32 s20, s20, 0x1000
	s_addc_u32 s21, s21, 0
	global_load_dwordx4 v[100:103], v39, s[10:11]
	global_load_dwordx4 v[104:107], v39, s[10:11] offset:1024
	global_load_dwordx4 v[108:111], v39, s[10:11] offset:2048
	global_load_dwordx4 v[112:115], v39, s[10:11] offset:3072
	s_add_u32 s10, s10, 0x1000
	s_addc_u32 s11, s11, 0
	s_waitcnt vmcnt(16)
	v_lshlrev_b32_e32 v60, 16, v116
	v_and_b32_e32 v61, 0xffff0000, v116
	v_pk_mul_f32 v[42:43], v[60:61], v[60:61]
	v_lshlrev_b32_e32 v62, 16, v117
	v_and_b32_e32 v63, 0xffff0000, v117
	v_pk_fma_f32 v[42:43], v[62:63], v[62:63], v[42:43]
	v_lshlrev_b32_e32 v64, 16, v118
	v_and_b32_e32 v65, 0xffff0000, v118
	v_pk_fma_f32 v[42:43], v[64:65], v[64:65], v[42:43]
	v_lshlrev_b32_e32 v66, 16, v119
	v_and_b32_e32 v67, 0xffff0000, v119
	v_pk_fma_f32 v[42:43], v[66:67], v[66:67], v[42:43]
	v_lshlrev_b32_e32 v60, 16, v120
	v_and_b32_e32 v61, 0xffff0000, v120
	v_pk_fma_f32 v[42:43], v[60:61], v[60:61], v[42:43]
	v_lshlrev_b32_e32 v62, 16, v121
	v_and_b32_e32 v63, 0xffff0000, v121
	v_pk_fma_f32 v[42:43], v[62:63], v[62:63], v[42:43]
	v_lshlrev_b32_e32 v64, 16, v122
	v_and_b32_e32 v65, 0xffff0000, v122
	v_pk_fma_f32 v[42:43], v[64:65], v[64:65], v[42:43]
	v_lshlrev_b32_e32 v66, 16, v123
	v_and_b32_e32 v67, 0xffff0000, v123
	v_pk_fma_f32 v[42:43], v[66:67], v[66:67], v[42:43]
	v_lshlrev_b32_e32 v60, 16, v124
	v_and_b32_e32 v61, 0xffff0000, v124
	v_pk_fma_f32 v[42:43], v[60:61], v[60:61], v[42:43]
	v_lshlrev_b32_e32 v62, 16, v125
	v_and_b32_e32 v63, 0xffff0000, v125
	v_pk_fma_f32 v[42:43], v[62:63], v[62:63], v[42:43]
	v_lshlrev_b32_e32 v64, 16, v126
	v_and_b32_e32 v65, 0xffff0000, v126
	v_pk_fma_f32 v[42:43], v[64:65], v[64:65], v[42:43]
	v_lshlrev_b32_e32 v66, 16, v127
	v_and_b32_e32 v67, 0xffff0000, v127
	v_pk_fma_f32 v[42:43], v[66:67], v[66:67], v[42:43]
	v_lshlrev_b32_e32 v60, 16, v128
	v_and_b32_e32 v61, 0xffff0000, v128
	v_pk_fma_f32 v[42:43], v[60:61], v[60:61], v[42:43]
	v_lshlrev_b32_e32 v62, 16, v129
	v_and_b32_e32 v63, 0xffff0000, v129
	v_pk_fma_f32 v[42:43], v[62:63], v[62:63], v[42:43]
	v_lshlrev_b32_e32 v64, 16, v130
	v_and_b32_e32 v65, 0xffff0000, v130
	v_pk_fma_f32 v[42:43], v[64:65], v[64:65], v[42:43]
	v_lshlrev_b32_e32 v66, 16, v131
	v_and_b32_e32 v67, 0xffff0000, v131
	v_pk_fma_f32 v[42:43], v[66:67], v[66:67], v[42:43]
	v_add_f32_e32 v42, v42, v43
	s_nop 1
	v_add_f32_dpp v42, v42, v42 quad_perm:[1,0,3,2] row_mask:0xf bank_mask:0xf
	s_nop 1
	v_add_f32_dpp v42, v42, v42 quad_perm:[2,3,0,1] row_mask:0xf bank_mask:0xf
	s_nop 1
	v_add_f32_dpp v42, v42, v42 row_half_mirror row_mask:0xf bank_mask:0xf
	s_nop 1
	v_add_f32_dpp v42, v42, v42 row_mirror row_mask:0xf bank_mask:0xf
	s_nop 1
	v_add_f32_dpp v42, v42, v42 row_bcast:15 row_mask:0xa bank_mask:0xf
	s_nop 1
	v_add_f32_dpp v42, v42, v42 row_bcast:31 row_mask:0xc bank_mask:0xf
	s_nop 1
	v_readlane_b32 s100, v42, 63
	s_nop 3
	v_mov_b32_e32 v44, s100
	v_fma_f32 v44, v44, v47, v224
	v_rsq_f32_e32 v45, v44
	s_nop 0
	v_mul_f32_e32 v46, v44, v45
	v_mul_f32_e32 v46, v46, v45
	v_fmaak_f32 v46, -0.5, v46, 0x3fc00000
	v_mul_f32_e32 v44, v45, v46
	v_mov_b32_e32 v45, v44
	v_lshlrev_b32_e32 v60, 16, v116
	v_and_b32_e32 v61, 0xffff0000, v116
	v_pk_mul_f32 v[60:61], v[60:61], v[44:45]
	v_pk_fma_f32 v[60:61], v[60:61], v[2:3], v[164:165]
	v_cvt_pk_bf16_f32 v116, v60, v61
	v_lshlrev_b32_e32 v62, 16, v117
	v_and_b32_e32 v63, 0xffff0000, v117
	v_pk_mul_f32 v[62:63], v[62:63], v[44:45]
	v_pk_fma_f32 v[62:63], v[62:63], v[4:5], v[166:167]
	v_cvt_pk_bf16_f32 v117, v62, v63
	v_lshlrev_b32_e32 v64, 16, v118
	v_and_b32_e32 v65, 0xffff0000, v118
	v_pk_mul_f32 v[64:65], v[64:65], v[44:45]
	v_pk_fma_f32 v[64:65], v[64:65], v[6:7], v[168:169]
	v_cvt_pk_bf16_f32 v118, v64, v65
	v_lshlrev_b32_e32 v66, 16, v119
	v_and_b32_e32 v67, 0xffff0000, v119
	v_pk_mul_f32 v[66:67], v[66:67], v[44:45]
	v_pk_fma_f32 v[66:67], v[66:67], v[8:9], v[170:171]
	v_cvt_pk_bf16_f32 v119, v66, v67
	v_lshlrev_b32_e32 v60, 16, v120
	v_and_b32_e32 v61, 0xffff0000, v120
	v_pk_mul_f32 v[60:61], v[60:61], v[44:45]
	v_pk_fma_f32 v[60:61], v[60:61], v[10:11], v[172:173]
	v_cvt_pk_bf16_f32 v120, v60, v61
	v_lshlrev_b32_e32 v62, 16, v121
	v_and_b32_e32 v63, 0xffff0000, v121
	v_pk_mul_f32 v[62:63], v[62:63], v[44:45]
	v_pk_fma_f32 v[62:63], v[62:63], v[12:13], v[174:175]
	v_cvt_pk_bf16_f32 v121, v62, v63
	v_lshlrev_b32_e32 v64, 16, v122
	v_and_b32_e32 v65, 0xffff0000, v122
	v_pk_mul_f32 v[64:65], v[64:65], v[44:45]
	v_pk_fma_f32 v[64:65], v[64:65], v[14:15], v[176:177]
	v_cvt_pk_bf16_f32 v122, v64, v65
	v_lshlrev_b32_e32 v66, 16, v123
	v_and_b32_e32 v67, 0xffff0000, v123
	v_pk_mul_f32 v[66:67], v[66:67], v[44:45]
	v_pk_fma_f32 v[66:67], v[66:67], v[16:17], v[178:179]
	v_cvt_pk_bf16_f32 v123, v66, v67
	v_lshlrev_b32_e32 v60, 16, v124
	v_and_b32_e32 v61, 0xffff0000, v124
	v_pk_mul_f32 v[60:61], v[60:61], v[44:45]
	v_pk_fma_f32 v[60:61], v[60:61], v[18:19], v[180:181]
	v_cvt_pk_bf16_f32 v124, v60, v61
	v_lshlrev_b32_e32 v62, 16, v125
	v_and_b32_e32 v63, 0xffff0000, v125
	v_pk_mul_f32 v[62:63], v[62:63], v[44:45]
	v_pk_fma_f32 v[62:63], v[62:63], v[20:21], v[182:183]
	v_cvt_pk_bf16_f32 v125, v62, v63
	v_lshlrev_b32_e32 v64, 16, v126
	v_and_b32_e32 v65, 0xffff0000, v126
	v_pk_mul_f32 v[64:65], v[64:65], v[44:45]
	v_pk_fma_f32 v[64:65], v[64:65], v[22:23], v[184:185]
	v_cvt_pk_bf16_f32 v126, v64, v65
	v_lshlrev_b32_e32 v66, 16, v127
	v_and_b32_e32 v67, 0xffff0000, v127
	v_pk_mul_f32 v[66:67], v[66:67], v[44:45]
	v_pk_fma_f32 v[66:67], v[66:67], v[24:25], v[186:187]
	v_cvt_pk_bf16_f32 v127, v66, v67
	v_lshlrev_b32_e32 v60, 16, v128
	v_and_b32_e32 v61, 0xffff0000, v128
	v_pk_mul_f32 v[60:61], v[60:61], v[44:45]
	v_pk_fma_f32 v[60:61], v[60:61], v[26:27], v[188:189]
	v_cvt_pk_bf16_f32 v128, v60, v61
	v_lshlrev_b32_e32 v62, 16, v129
	v_and_b32_e32 v63, 0xffff0000, v129
	v_pk_mul_f32 v[62:63], v[62:63], v[44:45]
	v_pk_fma_f32 v[62:63], v[62:63], v[28:29], v[190:191]
	v_cvt_pk_bf16_f32 v129, v62, v63
	v_lshlrev_b32_e32 v64, 16, v130
	v_and_b32_e32 v65, 0xffff0000, v130
	v_pk_mul_f32 v[64:65], v[64:65], v[44:45]
	v_pk_fma_f32 v[64:65], v[64:65], v[30:31], v[192:193]
	v_cvt_pk_bf16_f32 v130, v64, v65
	v_lshlrev_b32_e32 v66, 16, v131
	v_and_b32_e32 v67, 0xffff0000, v131
	v_pk_mul_f32 v[66:67], v[66:67], v[44:45]
	v_pk_fma_f32 v[66:67], v[66:67], v[32:33], v[194:195]
	v_cvt_pk_bf16_f32 v131, v66, v67
	global_store_dwordx4 v39, v[116:119], s[20:21]
	global_store_dwordx4 v39, v[120:123], s[20:21] offset:1024
	global_store_dwordx4 v39, v[124:127], s[20:21] offset:2048
	global_store_dwordx4 v39, v[128:131], s[20:21] offset:3072
	s_add_u32 s20, s20, 0x1000
	s_addc_u32 s21, s21, 0
	global_load_dwordx4 v[116:119], v39, s[10:11]
	global_load_dwordx4 v[120:123], v39, s[10:11] offset:1024
	global_load_dwordx4 v[124:127], v39, s[10:11] offset:2048
	global_load_dwordx4 v[128:131], v39, s[10:11] offset:3072
	s_add_u32 s10, s10, 0x1000
	s_addc_u32 s11, s11, 0
	s_waitcnt vmcnt(20)
	v_lshlrev_b32_e32 v60, 16, v132
	v_and_b32_e32 v61, 0xffff0000, v132
	v_pk_mul_f32 v[42:43], v[60:61], v[60:61]
	v_lshlrev_b32_e32 v62, 16, v133
	v_and_b32_e32 v63, 0xffff0000, v133
	v_pk_fma_f32 v[42:43], v[62:63], v[62:63], v[42:43]
	v_lshlrev_b32_e32 v64, 16, v134
	v_and_b32_e32 v65, 0xffff0000, v134
	v_pk_fma_f32 v[42:43], v[64:65], v[64:65], v[42:43]
	v_lshlrev_b32_e32 v66, 16, v135
	v_and_b32_e32 v67, 0xffff0000, v135
	v_pk_fma_f32 v[42:43], v[66:67], v[66:67], v[42:43]
	v_lshlrev_b32_e32 v60, 16, v136
	v_and_b32_e32 v61, 0xffff0000, v136
	v_pk_fma_f32 v[42:43], v[60:61], v[60:61], v[42:43]
	v_lshlrev_b32_e32 v62, 16, v137
	v_and_b32_e32 v63, 0xffff0000, v137
	v_pk_fma_f32 v[42:43], v[62:63], v[62:63], v[42:43]
	v_lshlrev_b32_e32 v64, 16, v138
	v_and_b32_e32 v65, 0xffff0000, v138
	v_pk_fma_f32 v[42:43], v[64:65], v[64:65], v[42:43]
	v_lshlrev_b32_e32 v66, 16, v139
	v_and_b32_e32 v67, 0xffff0000, v139
	v_pk_fma_f32 v[42:43], v[66:67], v[66:67], v[42:43]
	v_lshlrev_b32_e32 v60, 16, v140
	v_and_b32_e32 v61, 0xffff0000, v140
	v_pk_fma_f32 v[42:43], v[60:61], v[60:61], v[42:43]
	v_lshlrev_b32_e32 v62, 16, v141
	v_and_b32_e32 v63, 0xffff0000, v141
	v_pk_fma_f32 v[42:43], v[62:63], v[62:63], v[42:43]
	v_lshlrev_b32_e32 v64, 16, v142
	v_and_b32_e32 v65, 0xffff0000, v142
	v_pk_fma_f32 v[42:43], v[64:65], v[64:65], v[42:43]
	v_lshlrev_b32_e32 v66, 16, v143
	v_and_b32_e32 v67, 0xffff0000, v143
	v_pk_fma_f32 v[42:43], v[66:67], v[66:67], v[42:43]
	v_lshlrev_b32_e32 v60, 16, v144
	v_and_b32_e32 v61, 0xffff0000, v144
	v_pk_fma_f32 v[42:43], v[60:61], v[60:61], v[42:43]
	v_lshlrev_b32_e32 v62, 16, v145
	v_and_b32_e32 v63, 0xffff0000, v145
	v_pk_fma_f32 v[42:43], v[62:63], v[62:63], v[42:43]
	v_lshlrev_b32_e32 v64, 16, v146
	v_and_b32_e32 v65, 0xffff0000, v146
	v_pk_fma_f32 v[42:43], v[64:65], v[64:65], v[42:43]
	v_lshlrev_b32_e32 v66, 16, v147
	v_and_b32_e32 v67, 0xffff0000, v147
	v_pk_fma_f32 v[42:43], v[66:67], v[66:67], v[42:43]
	v_add_f32_e32 v42, v42, v43
	s_nop 1
	v_add_f32_dpp v42, v42, v42 quad_perm:[1,0,3,2] row_mask:0xf bank_mask:0xf
	s_nop 1
	v_add_f32_dpp v42, v42, v42 quad_perm:[2,3,0,1] row_mask:0xf bank_mask:0xf
	s_nop 1
	v_add_f32_dpp v42, v42, v42 row_half_mirror row_mask:0xf bank_mask:0xf
	s_nop 1
	v_add_f32_dpp v42, v42, v42 row_mirror row_mask:0xf bank_mask:0xf
	s_nop 1
	v_add_f32_dpp v42, v42, v42 row_bcast:15 row_mask:0xa bank_mask:0xf
	s_nop 1
	v_add_f32_dpp v42, v42, v42 row_bcast:31 row_mask:0xc bank_mask:0xf
	s_nop 1
	v_readlane_b32 s100, v42, 63
	s_nop 3
	v_mov_b32_e32 v44, s100
	v_fma_f32 v44, v44, v47, v224
	v_rsq_f32_e32 v45, v44
	s_nop 0
	v_mul_f32_e32 v46, v44, v45
	v_mul_f32_e32 v46, v46, v45
	v_fmaak_f32 v46, -0.5, v46, 0x3fc00000
	v_mul_f32_e32 v44, v45, v46
	v_mov_b32_e32 v45, v44
	v_lshlrev_b32_e32 v60, 16, v132
	v_and_b32_e32 v61, 0xffff0000, v132
	v_pk_mul_f32 v[60:61], v[60:61], v[44:45]
	v_pk_fma_f32 v[60:61], v[60:61], v[2:3], v[164:165]
	v_cvt_pk_bf16_f32 v132, v60, v61
	v_lshlrev_b32_e32 v62, 16, v133
	v_and_b32_e32 v63, 0xffff0000, v133
	v_pk_mul_f32 v[62:63], v[62:63], v[44:45]
	v_pk_fma_f32 v[62:63], v[62:63], v[4:5], v[166:167]
	v_cvt_pk_bf16_f32 v133, v62, v63
	v_lshlrev_b32_e32 v64, 16, v134
	v_and_b32_e32 v65, 0xffff0000, v134
	v_pk_mul_f32 v[64:65], v[64:65], v[44:45]
	v_pk_fma_f32 v[64:65], v[64:65], v[6:7], v[168:169]
	v_cvt_pk_bf16_f32 v134, v64, v65
	v_lshlrev_b32_e32 v66, 16, v135
	v_and_b32_e32 v67, 0xffff0000, v135
	v_pk_mul_f32 v[66:67], v[66:67], v[44:45]
	v_pk_fma_f32 v[66:67], v[66:67], v[8:9], v[170:171]
	v_cvt_pk_bf16_f32 v135, v66, v67
	v_lshlrev_b32_e32 v60, 16, v136
	v_and_b32_e32 v61, 0xffff0000, v136
	v_pk_mul_f32 v[60:61], v[60:61], v[44:45]
	v_pk_fma_f32 v[60:61], v[60:61], v[10:11], v[172:173]
	v_cvt_pk_bf16_f32 v136, v60, v61
	v_lshlrev_b32_e32 v62, 16, v137
	v_and_b32_e32 v63, 0xffff0000, v137
	v_pk_mul_f32 v[62:63], v[62:63], v[44:45]
	v_pk_fma_f32 v[62:63], v[62:63], v[12:13], v[174:175]
	v_cvt_pk_bf16_f32 v137, v62, v63
	v_lshlrev_b32_e32 v64, 16, v138
	v_and_b32_e32 v65, 0xffff0000, v138
	v_pk_mul_f32 v[64:65], v[64:65], v[44:45]
	v_pk_fma_f32 v[64:65], v[64:65], v[14:15], v[176:177]
	v_cvt_pk_bf16_f32 v138, v64, v65
	v_lshlrev_b32_e32 v66, 16, v139
	v_and_b32_e32 v67, 0xffff0000, v139
	v_pk_mul_f32 v[66:67], v[66:67], v[44:45]
	v_pk_fma_f32 v[66:67], v[66:67], v[16:17], v[178:179]
	v_cvt_pk_bf16_f32 v139, v66, v67
	v_lshlrev_b32_e32 v60, 16, v140
	v_and_b32_e32 v61, 0xffff0000, v140
	v_pk_mul_f32 v[60:61], v[60:61], v[44:45]
	v_pk_fma_f32 v[60:61], v[60:61], v[18:19], v[180:181]
	v_cvt_pk_bf16_f32 v140, v60, v61
	v_lshlrev_b32_e32 v62, 16, v141
	v_and_b32_e32 v63, 0xffff0000, v141
	v_pk_mul_f32 v[62:63], v[62:63], v[44:45]
	v_pk_fma_f32 v[62:63], v[62:63], v[20:21], v[182:183]
	v_cvt_pk_bf16_f32 v141, v62, v63
	v_lshlrev_b32_e32 v64, 16, v142
	v_and_b32_e32 v65, 0xffff0000, v142
	v_pk_mul_f32 v[64:65], v[64:65], v[44:45]
	v_pk_fma_f32 v[64:65], v[64:65], v[22:23], v[184:185]
	v_cvt_pk_bf16_f32 v142, v64, v65
	v_lshlrev_b32_e32 v66, 16, v143
	v_and_b32_e32 v67, 0xffff0000, v143
	v_pk_mul_f32 v[66:67], v[66:67], v[44:45]
	v_pk_fma_f32 v[66:67], v[66:67], v[24:25], v[186:187]
	v_cvt_pk_bf16_f32 v143, v66, v67
	v_lshlrev_b32_e32 v60, 16, v144
	v_and_b32_e32 v61, 0xffff0000, v144
	v_pk_mul_f32 v[60:61], v[60:61], v[44:45]
	v_pk_fma_f32 v[60:61], v[60:61], v[26:27], v[188:189]
	v_cvt_pk_bf16_f32 v144, v60, v61
	v_lshlrev_b32_e32 v62, 16, v145
	v_and_b32_e32 v63, 0xffff0000, v145
	v_pk_mul_f32 v[62:63], v[62:63], v[44:45]
	v_pk_fma_f32 v[62:63], v[62:63], v[28:29], v[190:191]
	v_cvt_pk_bf16_f32 v145, v62, v63
	v_lshlrev_b32_e32 v64, 16, v146
	v_and_b32_e32 v65, 0xffff0000, v146
	v_pk_mul_f32 v[64:65], v[64:65], v[44:45]
	v_pk_fma_f32 v[64:65], v[64:65], v[30:31], v[192:193]
	v_cvt_pk_bf16_f32 v146, v64, v65
	v_lshlrev_b32_e32 v66, 16, v147
	v_and_b32_e32 v67, 0xffff0000, v147
	v_pk_mul_f32 v[66:67], v[66:67], v[44:45]
	v_pk_fma_f32 v[66:67], v[66:67], v[32:33], v[194:195]
	v_cvt_pk_bf16_f32 v147, v66, v67
	global_store_dwordx4 v39, v[132:135], s[20:21]
	global_store_dwordx4 v39, v[136:139], s[20:21] offset:1024
	global_store_dwordx4 v39, v[140:143], s[20:21] offset:2048
	global_store_dwordx4 v39, v[144:147], s[20:21] offset:3072
	s_add_u32 s20, s20, 0x1000
	s_addc_u32 s21, s21, 0
	global_load_dwordx4 v[132:135], v39, s[10:11]
	global_load_dwordx4 v[136:139], v39, s[10:11] offset:1024
	global_load_dwordx4 v[140:143], v39, s[10:11] offset:2048
	global_load_dwordx4 v[144:147], v39, s[10:11] offset:3072
	s_add_u32 s10, s10, 0x1000
	s_addc_u32 s11, s11, 0
	s_waitcnt vmcnt(24)
	v_lshlrev_b32_e32 v60, 16, v148
	v_and_b32_e32 v61, 0xffff0000, v148
	v_pk_mul_f32 v[42:43], v[60:61], v[60:61]
	v_lshlrev_b32_e32 v62, 16, v149
	v_and_b32_e32 v63, 0xffff0000, v149
	v_pk_fma_f32 v[42:43], v[62:63], v[62:63], v[42:43]
	v_lshlrev_b32_e32 v64, 16, v150
	v_and_b32_e32 v65, 0xffff0000, v150
	v_pk_fma_f32 v[42:43], v[64:65], v[64:65], v[42:43]
	v_lshlrev_b32_e32 v66, 16, v151
	v_and_b32_e32 v67, 0xffff0000, v151
	v_pk_fma_f32 v[42:43], v[66:67], v[66:67], v[42:43]
	v_lshlrev_b32_e32 v60, 16, v152
	v_and_b32_e32 v61, 0xffff0000, v152
	v_pk_fma_f32 v[42:43], v[60:61], v[60:61], v[42:43]
	v_lshlrev_b32_e32 v62, 16, v153
	v_and_b32_e32 v63, 0xffff0000, v153
	v_pk_fma_f32 v[42:43], v[62:63], v[62:63], v[42:43]
	v_lshlrev_b32_e32 v64, 16, v154
	v_and_b32_e32 v65, 0xffff0000, v154
	v_pk_fma_f32 v[42:43], v[64:65], v[64:65], v[42:43]
	v_lshlrev_b32_e32 v66, 16, v155
	v_and_b32_e32 v67, 0xffff0000, v155
	v_pk_fma_f32 v[42:43], v[66:67], v[66:67], v[42:43]
	v_lshlrev_b32_e32 v60, 16, v156
	v_and_b32_e32 v61, 0xffff0000, v156
	v_pk_fma_f32 v[42:43], v[60:61], v[60:61], v[42:43]
	v_lshlrev_b32_e32 v62, 16, v157
	v_and_b32_e32 v63, 0xffff0000, v157
	v_pk_fma_f32 v[42:43], v[62:63], v[62:63], v[42:43]
	v_lshlrev_b32_e32 v64, 16, v158
	v_and_b32_e32 v65, 0xffff0000, v158
	v_pk_fma_f32 v[42:43], v[64:65], v[64:65], v[42:43]
	v_lshlrev_b32_e32 v66, 16, v159
	v_and_b32_e32 v67, 0xffff0000, v159
	v_pk_fma_f32 v[42:43], v[66:67], v[66:67], v[42:43]
	v_lshlrev_b32_e32 v60, 16, v160
	v_and_b32_e32 v61, 0xffff0000, v160
	v_pk_fma_f32 v[42:43], v[60:61], v[60:61], v[42:43]
	v_lshlrev_b32_e32 v62, 16, v161
	v_and_b32_e32 v63, 0xffff0000, v161
	v_pk_fma_f32 v[42:43], v[62:63], v[62:63], v[42:43]
	v_lshlrev_b32_e32 v64, 16, v162
	v_and_b32_e32 v65, 0xffff0000, v162
	v_pk_fma_f32 v[42:43], v[64:65], v[64:65], v[42:43]
	v_lshlrev_b32_e32 v66, 16, v163
	v_and_b32_e32 v67, 0xffff0000, v163
	v_pk_fma_f32 v[42:43], v[66:67], v[66:67], v[42:43]
	v_add_f32_e32 v42, v42, v43
	s_nop 1
	v_add_f32_dpp v42, v42, v42 quad_perm:[1,0,3,2] row_mask:0xf bank_mask:0xf
	s_nop 1
	v_add_f32_dpp v42, v42, v42 quad_perm:[2,3,0,1] row_mask:0xf bank_mask:0xf
	s_nop 1
	v_add_f32_dpp v42, v42, v42 row_half_mirror row_mask:0xf bank_mask:0xf
	s_nop 1
	v_add_f32_dpp v42, v42, v42 row_mirror row_mask:0xf bank_mask:0xf
	s_nop 1
	v_add_f32_dpp v42, v42, v42 row_bcast:15 row_mask:0xa bank_mask:0xf
	s_nop 1
	v_add_f32_dpp v42, v42, v42 row_bcast:31 row_mask:0xc bank_mask:0xf
	s_nop 1
	v_readlane_b32 s100, v42, 63
	s_nop 3
	v_mov_b32_e32 v44, s100
	v_fma_f32 v44, v44, v47, v224
	v_rsq_f32_e32 v45, v44
	s_nop 0
	v_mul_f32_e32 v46, v44, v45
	v_mul_f32_e32 v46, v46, v45
	v_fmaak_f32 v46, -0.5, v46, 0x3fc00000
	v_mul_f32_e32 v44, v45, v46
	v_mov_b32_e32 v45, v44
	v_lshlrev_b32_e32 v60, 16, v148
	v_and_b32_e32 v61, 0xffff0000, v148
	v_pk_mul_f32 v[60:61], v[60:61], v[44:45]
	v_pk_fma_f32 v[60:61], v[60:61], v[2:3], v[164:165]
	v_cvt_pk_bf16_f32 v148, v60, v61
	v_lshlrev_b32_e32 v62, 16, v149
	v_and_b32_e32 v63, 0xffff0000, v149
	v_pk_mul_f32 v[62:63], v[62:63], v[44:45]
	v_pk_fma_f32 v[62:63], v[62:63], v[4:5], v[166:167]
	v_cvt_pk_bf16_f32 v149, v62, v63
	v_lshlrev_b32_e32 v64, 16, v150
	v_and_b32_e32 v65, 0xffff0000, v150
	v_pk_mul_f32 v[64:65], v[64:65], v[44:45]
	v_pk_fma_f32 v[64:65], v[64:65], v[6:7], v[168:169]
	v_cvt_pk_bf16_f32 v150, v64, v65
	v_lshlrev_b32_e32 v66, 16, v151
	v_and_b32_e32 v67, 0xffff0000, v151
	v_pk_mul_f32 v[66:67], v[66:67], v[44:45]
	v_pk_fma_f32 v[66:67], v[66:67], v[8:9], v[170:171]
	v_cvt_pk_bf16_f32 v151, v66, v67
	v_lshlrev_b32_e32 v60, 16, v152
	v_and_b32_e32 v61, 0xffff0000, v152
	v_pk_mul_f32 v[60:61], v[60:61], v[44:45]
	v_pk_fma_f32 v[60:61], v[60:61], v[10:11], v[172:173]
	v_cvt_pk_bf16_f32 v152, v60, v61
	v_lshlrev_b32_e32 v62, 16, v153
	v_and_b32_e32 v63, 0xffff0000, v153
	v_pk_mul_f32 v[62:63], v[62:63], v[44:45]
	v_pk_fma_f32 v[62:63], v[62:63], v[12:13], v[174:175]
	v_cvt_pk_bf16_f32 v153, v62, v63
	v_lshlrev_b32_e32 v64, 16, v154
	v_and_b32_e32 v65, 0xffff0000, v154
	v_pk_mul_f32 v[64:65], v[64:65], v[44:45]
	v_pk_fma_f32 v[64:65], v[64:65], v[14:15], v[176:177]
	v_cvt_pk_bf16_f32 v154, v64, v65
	v_lshlrev_b32_e32 v66, 16, v155
	v_and_b32_e32 v67, 0xffff0000, v155
	v_pk_mul_f32 v[66:67], v[66:67], v[44:45]
	v_pk_fma_f32 v[66:67], v[66:67], v[16:17], v[178:179]
	v_cvt_pk_bf16_f32 v155, v66, v67
	v_lshlrev_b32_e32 v60, 16, v156
	v_and_b32_e32 v61, 0xffff0000, v156
	v_pk_mul_f32 v[60:61], v[60:61], v[44:45]
	v_pk_fma_f32 v[60:61], v[60:61], v[18:19], v[180:181]
	v_cvt_pk_bf16_f32 v156, v60, v61
	v_lshlrev_b32_e32 v62, 16, v157
	v_and_b32_e32 v63, 0xffff0000, v157
	v_pk_mul_f32 v[62:63], v[62:63], v[44:45]
	v_pk_fma_f32 v[62:63], v[62:63], v[20:21], v[182:183]
	v_cvt_pk_bf16_f32 v157, v62, v63
	v_lshlrev_b32_e32 v64, 16, v158
	v_and_b32_e32 v65, 0xffff0000, v158
	v_pk_mul_f32 v[64:65], v[64:65], v[44:45]
	v_pk_fma_f32 v[64:65], v[64:65], v[22:23], v[184:185]
	v_cvt_pk_bf16_f32 v158, v64, v65
	v_lshlrev_b32_e32 v66, 16, v159
	v_and_b32_e32 v67, 0xffff0000, v159
	v_pk_mul_f32 v[66:67], v[66:67], v[44:45]
	v_pk_fma_f32 v[66:67], v[66:67], v[24:25], v[186:187]
	v_cvt_pk_bf16_f32 v159, v66, v67
	v_lshlrev_b32_e32 v60, 16, v160
	v_and_b32_e32 v61, 0xffff0000, v160
	v_pk_mul_f32 v[60:61], v[60:61], v[44:45]
	v_pk_fma_f32 v[60:61], v[60:61], v[26:27], v[188:189]
	v_cvt_pk_bf16_f32 v160, v60, v61
	v_lshlrev_b32_e32 v62, 16, v161
	v_and_b32_e32 v63, 0xffff0000, v161
	v_pk_mul_f32 v[62:63], v[62:63], v[44:45]
	v_pk_fma_f32 v[62:63], v[62:63], v[28:29], v[190:191]
	v_cvt_pk_bf16_f32 v161, v62, v63
	v_lshlrev_b32_e32 v64, 16, v162
	v_and_b32_e32 v65, 0xffff0000, v162
	v_pk_mul_f32 v[64:65], v[64:65], v[44:45]
	v_pk_fma_f32 v[64:65], v[64:65], v[30:31], v[192:193]
	v_cvt_pk_bf16_f32 v162, v64, v65
	v_lshlrev_b32_e32 v66, 16, v163
	v_and_b32_e32 v67, 0xffff0000, v163
	v_pk_mul_f32 v[66:67], v[66:67], v[44:45]
	v_pk_fma_f32 v[66:67], v[66:67], v[32:33], v[194:195]
	v_cvt_pk_bf16_f32 v163, v66, v67
	global_store_dwordx4 v39, v[148:151], s[20:21]
	global_store_dwordx4 v39, v[152:155], s[20:21] offset:1024
	global_store_dwordx4 v39, v[156:159], s[20:21] offset:2048
	global_store_dwordx4 v39, v[160:163], s[20:21] offset:3072
	s_add_u32 s20, s20, 0x1000
	s_addc_u32 s21, s21, 0
	global_load_dwordx4 v[148:151], v39, s[10:11]
	global_load_dwordx4 v[152:155], v39, s[10:11] offset:1024
	global_load_dwordx4 v[156:159], v39, s[10:11] offset:2048
	global_load_dwordx4 v[160:163], v39, s[10:11] offset:3072
	s_add_u32 s10, s10, 0x1000
	s_addc_u32 s11, s11, 0
	s_waitcnt vmcnt(24)
	v_lshlrev_b32_e32 v60, 16, v100
	v_and_b32_e32 v61, 0xffff0000, v100
	v_pk_mul_f32 v[42:43], v[60:61], v[60:61]
	v_lshlrev_b32_e32 v62, 16, v101
	v_and_b32_e32 v63, 0xffff0000, v101
	v_pk_fma_f32 v[42:43], v[62:63], v[62:63], v[42:43]
	v_lshlrev_b32_e32 v64, 16, v102
	v_and_b32_e32 v65, 0xffff0000, v102
	v_pk_fma_f32 v[42:43], v[64:65], v[64:65], v[42:43]
	v_lshlrev_b32_e32 v66, 16, v103
	v_and_b32_e32 v67, 0xffff0000, v103
	v_pk_fma_f32 v[42:43], v[66:67], v[66:67], v[42:43]
	v_lshlrev_b32_e32 v60, 16, v104
	v_and_b32_e32 v61, 0xffff0000, v104
	v_pk_fma_f32 v[42:43], v[60:61], v[60:61], v[42:43]
	v_lshlrev_b32_e32 v62, 16, v105
	v_and_b32_e32 v63, 0xffff0000, v105
	v_pk_fma_f32 v[42:43], v[62:63], v[62:63], v[42:43]
	v_lshlrev_b32_e32 v64, 16, v106
	v_and_b32_e32 v65, 0xffff0000, v106
	v_pk_fma_f32 v[42:43], v[64:65], v[64:65], v[42:43]
	v_lshlrev_b32_e32 v66, 16, v107
	v_and_b32_e32 v67, 0xffff0000, v107
	v_pk_fma_f32 v[42:43], v[66:67], v[66:67], v[42:43]
	v_lshlrev_b32_e32 v60, 16, v108
	v_and_b32_e32 v61, 0xffff0000, v108
	v_pk_fma_f32 v[42:43], v[60:61], v[60:61], v[42:43]
	v_lshlrev_b32_e32 v62, 16, v109
	v_and_b32_e32 v63, 0xffff0000, v109
	v_pk_fma_f32 v[42:43], v[62:63], v[62:63], v[42:43]
	v_lshlrev_b32_e32 v64, 16, v110
	v_and_b32_e32 v65, 0xffff0000, v110
	v_pk_fma_f32 v[42:43], v[64:65], v[64:65], v[42:43]
	v_lshlrev_b32_e32 v66, 16, v111
	v_and_b32_e32 v67, 0xffff0000, v111
	v_pk_fma_f32 v[42:43], v[66:67], v[66:67], v[42:43]
	v_lshlrev_b32_e32 v60, 16, v112
	v_and_b32_e32 v61, 0xffff0000, v112
	v_pk_fma_f32 v[42:43], v[60:61], v[60:61], v[42:43]
	v_lshlrev_b32_e32 v62, 16, v113
	v_and_b32_e32 v63, 0xffff0000, v113
	v_pk_fma_f32 v[42:43], v[62:63], v[62:63], v[42:43]
	v_lshlrev_b32_e32 v64, 16, v114
	v_and_b32_e32 v65, 0xffff0000, v114
	v_pk_fma_f32 v[42:43], v[64:65], v[64:65], v[42:43]
	v_lshlrev_b32_e32 v66, 16, v115
	v_and_b32_e32 v67, 0xffff0000, v115
	v_pk_fma_f32 v[42:43], v[66:67], v[66:67], v[42:43]
	v_add_f32_e32 v42, v42, v43
	s_nop 1
	v_add_f32_dpp v42, v42, v42 quad_perm:[1,0,3,2] row_mask:0xf bank_mask:0xf
	s_nop 1
	v_add_f32_dpp v42, v42, v42 quad_perm:[2,3,0,1] row_mask:0xf bank_mask:0xf
	s_nop 1
	v_add_f32_dpp v42, v42, v42 row_half_mirror row_mask:0xf bank_mask:0xf
	s_nop 1
	v_add_f32_dpp v42, v42, v42 row_mirror row_mask:0xf bank_mask:0xf
	s_nop 1
	v_add_f32_dpp v42, v42, v42 row_bcast:15 row_mask:0xa bank_mask:0xf
	s_nop 1
	v_add_f32_dpp v42, v42, v42 row_bcast:31 row_mask:0xc bank_mask:0xf
	s_nop 1
	v_readlane_b32 s100, v42, 63
	s_nop 3
	v_mov_b32_e32 v44, s100
	v_fma_f32 v44, v44, v47, v224
	v_rsq_f32_e32 v45, v44
	s_nop 0
	v_mul_f32_e32 v46, v44, v45
	v_mul_f32_e32 v46, v46, v45
	v_fmaak_f32 v46, -0.5, v46, 0x3fc00000
	v_mul_f32_e32 v44, v45, v46
	v_mov_b32_e32 v45, v44
	v_lshlrev_b32_e32 v60, 16, v100
	v_and_b32_e32 v61, 0xffff0000, v100
	v_pk_mul_f32 v[60:61], v[60:61], v[44:45]
	v_pk_fma_f32 v[60:61], v[60:61], v[2:3], v[164:165]
	v_cvt_pk_bf16_f32 v100, v60, v61
	v_lshlrev_b32_e32 v62, 16, v101
	v_and_b32_e32 v63, 0xffff0000, v101
	v_pk_mul_f32 v[62:63], v[62:63], v[44:45]
	v_pk_fma_f32 v[62:63], v[62:63], v[4:5], v[166:167]
	v_cvt_pk_bf16_f32 v101, v62, v63
	v_lshlrev_b32_e32 v64, 16, v102
	v_and_b32_e32 v65, 0xffff0000, v102
	v_pk_mul_f32 v[64:65], v[64:65], v[44:45]
	v_pk_fma_f32 v[64:65], v[64:65], v[6:7], v[168:169]
	v_cvt_pk_bf16_f32 v102, v64, v65
	v_lshlrev_b32_e32 v66, 16, v103
	v_and_b32_e32 v67, 0xffff0000, v103
	v_pk_mul_f32 v[66:67], v[66:67], v[44:45]
	v_pk_fma_f32 v[66:67], v[66:67], v[8:9], v[170:171]
	v_cvt_pk_bf16_f32 v103, v66, v67
	v_lshlrev_b32_e32 v60, 16, v104
	v_and_b32_e32 v61, 0xffff0000, v104
	v_pk_mul_f32 v[60:61], v[60:61], v[44:45]
	v_pk_fma_f32 v[60:61], v[60:61], v[10:11], v[172:173]
	v_cvt_pk_bf16_f32 v104, v60, v61
	v_lshlrev_b32_e32 v62, 16, v105
	v_and_b32_e32 v63, 0xffff0000, v105
	v_pk_mul_f32 v[62:63], v[62:63], v[44:45]
	v_pk_fma_f32 v[62:63], v[62:63], v[12:13], v[174:175]
	v_cvt_pk_bf16_f32 v105, v62, v63
	v_lshlrev_b32_e32 v64, 16, v106
	v_and_b32_e32 v65, 0xffff0000, v106
	v_pk_mul_f32 v[64:65], v[64:65], v[44:45]
	v_pk_fma_f32 v[64:65], v[64:65], v[14:15], v[176:177]
	v_cvt_pk_bf16_f32 v106, v64, v65
	v_lshlrev_b32_e32 v66, 16, v107
	v_and_b32_e32 v67, 0xffff0000, v107
	v_pk_mul_f32 v[66:67], v[66:67], v[44:45]
	v_pk_fma_f32 v[66:67], v[66:67], v[16:17], v[178:179]
	v_cvt_pk_bf16_f32 v107, v66, v67
	v_lshlrev_b32_e32 v60, 16, v108
	v_and_b32_e32 v61, 0xffff0000, v108
	v_pk_mul_f32 v[60:61], v[60:61], v[44:45]
	v_pk_fma_f32 v[60:61], v[60:61], v[18:19], v[180:181]
	v_cvt_pk_bf16_f32 v108, v60, v61
	v_lshlrev_b32_e32 v62, 16, v109
	v_and_b32_e32 v63, 0xffff0000, v109
	v_pk_mul_f32 v[62:63], v[62:63], v[44:45]
	v_pk_fma_f32 v[62:63], v[62:63], v[20:21], v[182:183]
	v_cvt_pk_bf16_f32 v109, v62, v63
	v_lshlrev_b32_e32 v64, 16, v110
	v_and_b32_e32 v65, 0xffff0000, v110
	v_pk_mul_f32 v[64:65], v[64:65], v[44:45]
	v_pk_fma_f32 v[64:65], v[64:65], v[22:23], v[184:185]
	v_cvt_pk_bf16_f32 v110, v64, v65
	v_lshlrev_b32_e32 v66, 16, v111
	v_and_b32_e32 v67, 0xffff0000, v111
	v_pk_mul_f32 v[66:67], v[66:67], v[44:45]
	v_pk_fma_f32 v[66:67], v[66:67], v[24:25], v[186:187]
	v_cvt_pk_bf16_f32 v111, v66, v67
	v_lshlrev_b32_e32 v60, 16, v112
	v_and_b32_e32 v61, 0xffff0000, v112
	v_pk_mul_f32 v[60:61], v[60:61], v[44:45]
	v_pk_fma_f32 v[60:61], v[60:61], v[26:27], v[188:189]
	v_cvt_pk_bf16_f32 v112, v60, v61
	v_lshlrev_b32_e32 v62, 16, v113
	v_and_b32_e32 v63, 0xffff0000, v113
	v_pk_mul_f32 v[62:63], v[62:63], v[44:45]
	v_pk_fma_f32 v[62:63], v[62:63], v[28:29], v[190:191]
	v_cvt_pk_bf16_f32 v113, v62, v63
	v_lshlrev_b32_e32 v64, 16, v114
	v_and_b32_e32 v65, 0xffff0000, v114
	v_pk_mul_f32 v[64:65], v[64:65], v[44:45]
	v_pk_fma_f32 v[64:65], v[64:65], v[30:31], v[192:193]
	v_cvt_pk_bf16_f32 v114, v64, v65
	v_lshlrev_b32_e32 v66, 16, v115
	v_and_b32_e32 v67, 0xffff0000, v115
	v_pk_mul_f32 v[66:67], v[66:67], v[44:45]
	v_pk_fma_f32 v[66:67], v[66:67], v[32:33], v[194:195]
	v_cvt_pk_bf16_f32 v115, v66, v67
	global_store_dwordx4 v39, v[100:103], s[20:21]
	global_store_dwordx4 v39, v[104:107], s[20:21] offset:1024
	global_store_dwordx4 v39, v[108:111], s[20:21] offset:2048
	global_store_dwordx4 v39, v[112:115], s[20:21] offset:3072
	s_add_u32 s20, s20, 0x1000
	s_addc_u32 s21, s21, 0
	s_waitcnt vmcnt(20)
	v_lshlrev_b32_e32 v60, 16, v116
	v_and_b32_e32 v61, 0xffff0000, v116
	v_pk_mul_f32 v[42:43], v[60:61], v[60:61]
	v_lshlrev_b32_e32 v62, 16, v117
	v_and_b32_e32 v63, 0xffff0000, v117
	v_pk_fma_f32 v[42:43], v[62:63], v[62:63], v[42:43]
	v_lshlrev_b32_e32 v64, 16, v118
	v_and_b32_e32 v65, 0xffff0000, v118
	v_pk_fma_f32 v[42:43], v[64:65], v[64:65], v[42:43]
	v_lshlrev_b32_e32 v66, 16, v119
	v_and_b32_e32 v67, 0xffff0000, v119
	v_pk_fma_f32 v[42:43], v[66:67], v[66:67], v[42:43]
	v_lshlrev_b32_e32 v60, 16, v120
	v_and_b32_e32 v61, 0xffff0000, v120
	v_pk_fma_f32 v[42:43], v[60:61], v[60:61], v[42:43]
	v_lshlrev_b32_e32 v62, 16, v121
	v_and_b32_e32 v63, 0xffff0000, v121
	v_pk_fma_f32 v[42:43], v[62:63], v[62:63], v[42:43]
	v_lshlrev_b32_e32 v64, 16, v122
	v_and_b32_e32 v65, 0xffff0000, v122
	v_pk_fma_f32 v[42:43], v[64:65], v[64:65], v[42:43]
	v_lshlrev_b32_e32 v66, 16, v123
	v_and_b32_e32 v67, 0xffff0000, v123
	v_pk_fma_f32 v[42:43], v[66:67], v[66:67], v[42:43]
	v_lshlrev_b32_e32 v60, 16, v124
	v_and_b32_e32 v61, 0xffff0000, v124
	v_pk_fma_f32 v[42:43], v[60:61], v[60:61], v[42:43]
	v_lshlrev_b32_e32 v62, 16, v125
	v_and_b32_e32 v63, 0xffff0000, v125
	v_pk_fma_f32 v[42:43], v[62:63], v[62:63], v[42:43]
	v_lshlrev_b32_e32 v64, 16, v126
	v_and_b32_e32 v65, 0xffff0000, v126
	v_pk_fma_f32 v[42:43], v[64:65], v[64:65], v[42:43]
	v_lshlrev_b32_e32 v66, 16, v127
	v_and_b32_e32 v67, 0xffff0000, v127
	v_pk_fma_f32 v[42:43], v[66:67], v[66:67], v[42:43]
	v_lshlrev_b32_e32 v60, 16, v128
	v_and_b32_e32 v61, 0xffff0000, v128
	v_pk_fma_f32 v[42:43], v[60:61], v[60:61], v[42:43]
	v_lshlrev_b32_e32 v62, 16, v129
	v_and_b32_e32 v63, 0xffff0000, v129
	v_pk_fma_f32 v[42:43], v[62:63], v[62:63], v[42:43]
	v_lshlrev_b32_e32 v64, 16, v130
	v_and_b32_e32 v65, 0xffff0000, v130
	v_pk_fma_f32 v[42:43], v[64:65], v[64:65], v[42:43]
	v_lshlrev_b32_e32 v66, 16, v131
	v_and_b32_e32 v67, 0xffff0000, v131
	v_pk_fma_f32 v[42:43], v[66:67], v[66:67], v[42:43]
	v_add_f32_e32 v42, v42, v43
	s_nop 1
	v_add_f32_dpp v42, v42, v42 quad_perm:[1,0,3,2] row_mask:0xf bank_mask:0xf
	s_nop 1
	v_add_f32_dpp v42, v42, v42 quad_perm:[2,3,0,1] row_mask:0xf bank_mask:0xf
	s_nop 1
	v_add_f32_dpp v42, v42, v42 row_half_mirror row_mask:0xf bank_mask:0xf
	s_nop 1
	v_add_f32_dpp v42, v42, v42 row_mirror row_mask:0xf bank_mask:0xf
	s_nop 1
	v_add_f32_dpp v42, v42, v42 row_bcast:15 row_mask:0xa bank_mask:0xf
	s_nop 1
	v_add_f32_dpp v42, v42, v42 row_bcast:31 row_mask:0xc bank_mask:0xf
	s_nop 1
	v_readlane_b32 s100, v42, 63
	s_nop 3
	v_mov_b32_e32 v44, s100
	v_fma_f32 v44, v44, v47, v224
	v_rsq_f32_e32 v45, v44
	s_nop 0
	v_mul_f32_e32 v46, v44, v45
	v_mul_f32_e32 v46, v46, v45
	v_fmaak_f32 v46, -0.5, v46, 0x3fc00000
	v_mul_f32_e32 v44, v45, v46
	v_mov_b32_e32 v45, v44
	v_lshlrev_b32_e32 v60, 16, v116
	v_and_b32_e32 v61, 0xffff0000, v116
	v_pk_mul_f32 v[60:61], v[60:61], v[44:45]
	v_pk_fma_f32 v[60:61], v[60:61], v[2:3], v[164:165]
	v_cvt_pk_bf16_f32 v116, v60, v61
	v_lshlrev_b32_e32 v62, 16, v117
	v_and_b32_e32 v63, 0xffff0000, v117
	v_pk_mul_f32 v[62:63], v[62:63], v[44:45]
	v_pk_fma_f32 v[62:63], v[62:63], v[4:5], v[166:167]
	v_cvt_pk_bf16_f32 v117, v62, v63
	v_lshlrev_b32_e32 v64, 16, v118
	v_and_b32_e32 v65, 0xffff0000, v118
	v_pk_mul_f32 v[64:65], v[64:65], v[44:45]
	v_pk_fma_f32 v[64:65], v[64:65], v[6:7], v[168:169]
	v_cvt_pk_bf16_f32 v118, v64, v65
	v_lshlrev_b32_e32 v66, 16, v119
	v_and_b32_e32 v67, 0xffff0000, v119
	v_pk_mul_f32 v[66:67], v[66:67], v[44:45]
	v_pk_fma_f32 v[66:67], v[66:67], v[8:9], v[170:171]
	v_cvt_pk_bf16_f32 v119, v66, v67
	v_lshlrev_b32_e32 v60, 16, v120
	v_and_b32_e32 v61, 0xffff0000, v120
	v_pk_mul_f32 v[60:61], v[60:61], v[44:45]
	v_pk_fma_f32 v[60:61], v[60:61], v[10:11], v[172:173]
	v_cvt_pk_bf16_f32 v120, v60, v61
	v_lshlrev_b32_e32 v62, 16, v121
	v_and_b32_e32 v63, 0xffff0000, v121
	v_pk_mul_f32 v[62:63], v[62:63], v[44:45]
	v_pk_fma_f32 v[62:63], v[62:63], v[12:13], v[174:175]
	v_cvt_pk_bf16_f32 v121, v62, v63
	v_lshlrev_b32_e32 v64, 16, v122
	v_and_b32_e32 v65, 0xffff0000, v122
	v_pk_mul_f32 v[64:65], v[64:65], v[44:45]
	v_pk_fma_f32 v[64:65], v[64:65], v[14:15], v[176:177]
	v_cvt_pk_bf16_f32 v122, v64, v65
	v_lshlrev_b32_e32 v66, 16, v123
	v_and_b32_e32 v67, 0xffff0000, v123
	v_pk_mul_f32 v[66:67], v[66:67], v[44:45]
	v_pk_fma_f32 v[66:67], v[66:67], v[16:17], v[178:179]
	v_cvt_pk_bf16_f32 v123, v66, v67
	v_lshlrev_b32_e32 v60, 16, v124
	v_and_b32_e32 v61, 0xffff0000, v124
	v_pk_mul_f32 v[60:61], v[60:61], v[44:45]
	v_pk_fma_f32 v[60:61], v[60:61], v[18:19], v[180:181]
	v_cvt_pk_bf16_f32 v124, v60, v61
	v_lshlrev_b32_e32 v62, 16, v125
	v_and_b32_e32 v63, 0xffff0000, v125
	v_pk_mul_f32 v[62:63], v[62:63], v[44:45]
	v_pk_fma_f32 v[62:63], v[62:63], v[20:21], v[182:183]
	v_cvt_pk_bf16_f32 v125, v62, v63
	v_lshlrev_b32_e32 v64, 16, v126
	v_and_b32_e32 v65, 0xffff0000, v126
	v_pk_mul_f32 v[64:65], v[64:65], v[44:45]
	v_pk_fma_f32 v[64:65], v[64:65], v[22:23], v[184:185]
	v_cvt_pk_bf16_f32 v126, v64, v65
	v_lshlrev_b32_e32 v66, 16, v127
	v_and_b32_e32 v67, 0xffff0000, v127
	v_pk_mul_f32 v[66:67], v[66:67], v[44:45]
	v_pk_fma_f32 v[66:67], v[66:67], v[24:25], v[186:187]
	v_cvt_pk_bf16_f32 v127, v66, v67
	v_lshlrev_b32_e32 v60, 16, v128
	v_and_b32_e32 v61, 0xffff0000, v128
	v_pk_mul_f32 v[60:61], v[60:61], v[44:45]
	v_pk_fma_f32 v[60:61], v[60:61], v[26:27], v[188:189]
	v_cvt_pk_bf16_f32 v128, v60, v61
	v_lshlrev_b32_e32 v62, 16, v129
	v_and_b32_e32 v63, 0xffff0000, v129
	v_pk_mul_f32 v[62:63], v[62:63], v[44:45]
	v_pk_fma_f32 v[62:63], v[62:63], v[28:29], v[190:191]
	v_cvt_pk_bf16_f32 v129, v62, v63
	v_lshlrev_b32_e32 v64, 16, v130
	v_and_b32_e32 v65, 0xffff0000, v130
	v_pk_mul_f32 v[64:65], v[64:65], v[44:45]
	v_pk_fma_f32 v[64:65], v[64:65], v[30:31], v[192:193]
	v_cvt_pk_bf16_f32 v130, v64, v65
	v_lshlrev_b32_e32 v66, 16, v131
	v_and_b32_e32 v67, 0xffff0000, v131
	v_pk_mul_f32 v[66:67], v[66:67], v[44:45]
	v_pk_fma_f32 v[66:67], v[66:67], v[32:33], v[194:195]
	v_cvt_pk_bf16_f32 v131, v66, v67
	global_store_dwordx4 v39, v[116:119], s[20:21]
	global_store_dwordx4 v39, v[120:123], s[20:21] offset:1024
	global_store_dwordx4 v39, v[124:127], s[20:21] offset:2048
	global_store_dwordx4 v39, v[128:131], s[20:21] offset:3072
	s_add_u32 s20, s20, 0x1000
	s_addc_u32 s21, s21, 0
	s_waitcnt vmcnt(16)
	v_lshlrev_b32_e32 v60, 16, v132
	v_and_b32_e32 v61, 0xffff0000, v132
	v_pk_mul_f32 v[42:43], v[60:61], v[60:61]
	v_lshlrev_b32_e32 v62, 16, v133
	v_and_b32_e32 v63, 0xffff0000, v133
	v_pk_fma_f32 v[42:43], v[62:63], v[62:63], v[42:43]
	v_lshlrev_b32_e32 v64, 16, v134
	v_and_b32_e32 v65, 0xffff0000, v134
	v_pk_fma_f32 v[42:43], v[64:65], v[64:65], v[42:43]
	v_lshlrev_b32_e32 v66, 16, v135
	v_and_b32_e32 v67, 0xffff0000, v135
	v_pk_fma_f32 v[42:43], v[66:67], v[66:67], v[42:43]
	v_lshlrev_b32_e32 v60, 16, v136
	v_and_b32_e32 v61, 0xffff0000, v136
	v_pk_fma_f32 v[42:43], v[60:61], v[60:61], v[42:43]
	v_lshlrev_b32_e32 v62, 16, v137
	v_and_b32_e32 v63, 0xffff0000, v137
	v_pk_fma_f32 v[42:43], v[62:63], v[62:63], v[42:43]
	v_lshlrev_b32_e32 v64, 16, v138
	v_and_b32_e32 v65, 0xffff0000, v138
	v_pk_fma_f32 v[42:43], v[64:65], v[64:65], v[42:43]
	v_lshlrev_b32_e32 v66, 16, v139
	v_and_b32_e32 v67, 0xffff0000, v139
	v_pk_fma_f32 v[42:43], v[66:67], v[66:67], v[42:43]
	v_lshlrev_b32_e32 v60, 16, v140
	v_and_b32_e32 v61, 0xffff0000, v140
	v_pk_fma_f32 v[42:43], v[60:61], v[60:61], v[42:43]
	v_lshlrev_b32_e32 v62, 16, v141
	v_and_b32_e32 v63, 0xffff0000, v141
	v_pk_fma_f32 v[42:43], v[62:63], v[62:63], v[42:43]
	v_lshlrev_b32_e32 v64, 16, v142
	v_and_b32_e32 v65, 0xffff0000, v142
	v_pk_fma_f32 v[42:43], v[64:65], v[64:65], v[42:43]
	v_lshlrev_b32_e32 v66, 16, v143
	v_and_b32_e32 v67, 0xffff0000, v143
	v_pk_fma_f32 v[42:43], v[66:67], v[66:67], v[42:43]
	v_lshlrev_b32_e32 v60, 16, v144
	v_and_b32_e32 v61, 0xffff0000, v144
	v_pk_fma_f32 v[42:43], v[60:61], v[60:61], v[42:43]
	v_lshlrev_b32_e32 v62, 16, v145
	v_and_b32_e32 v63, 0xffff0000, v145
	v_pk_fma_f32 v[42:43], v[62:63], v[62:63], v[42:43]
	v_lshlrev_b32_e32 v64, 16, v146
	v_and_b32_e32 v65, 0xffff0000, v146
	v_pk_fma_f32 v[42:43], v[64:65], v[64:65], v[42:43]
	v_lshlrev_b32_e32 v66, 16, v147
	v_and_b32_e32 v67, 0xffff0000, v147
	v_pk_fma_f32 v[42:43], v[66:67], v[66:67], v[42:43]
	v_add_f32_e32 v42, v42, v43
	s_nop 1
	v_add_f32_dpp v42, v42, v42 quad_perm:[1,0,3,2] row_mask:0xf bank_mask:0xf
	s_nop 1
	v_add_f32_dpp v42, v42, v42 quad_perm:[2,3,0,1] row_mask:0xf bank_mask:0xf
	s_nop 1
	v_add_f32_dpp v42, v42, v42 row_half_mirror row_mask:0xf bank_mask:0xf
	s_nop 1
	v_add_f32_dpp v42, v42, v42 row_mirror row_mask:0xf bank_mask:0xf
	s_nop 1
	v_add_f32_dpp v42, v42, v42 row_bcast:15 row_mask:0xa bank_mask:0xf
	s_nop 1
	v_add_f32_dpp v42, v42, v42 row_bcast:31 row_mask:0xc bank_mask:0xf
	s_nop 1
	v_readlane_b32 s100, v42, 63
	s_nop 3
	v_mov_b32_e32 v44, s100
	v_fma_f32 v44, v44, v47, v224
	v_rsq_f32_e32 v45, v44
	s_nop 0
	v_mul_f32_e32 v46, v44, v45
	v_mul_f32_e32 v46, v46, v45
	v_fmaak_f32 v46, -0.5, v46, 0x3fc00000
	v_mul_f32_e32 v44, v45, v46
	v_mov_b32_e32 v45, v44
	v_lshlrev_b32_e32 v60, 16, v132
	v_and_b32_e32 v61, 0xffff0000, v132
	v_pk_mul_f32 v[60:61], v[60:61], v[44:45]
	v_pk_fma_f32 v[60:61], v[60:61], v[2:3], v[164:165]
	v_cvt_pk_bf16_f32 v132, v60, v61
	v_lshlrev_b32_e32 v62, 16, v133
	v_and_b32_e32 v63, 0xffff0000, v133
	v_pk_mul_f32 v[62:63], v[62:63], v[44:45]
	v_pk_fma_f32 v[62:63], v[62:63], v[4:5], v[166:167]
	v_cvt_pk_bf16_f32 v133, v62, v63
	v_lshlrev_b32_e32 v64, 16, v134
	v_and_b32_e32 v65, 0xffff0000, v134
	v_pk_mul_f32 v[64:65], v[64:65], v[44:45]
	v_pk_fma_f32 v[64:65], v[64:65], v[6:7], v[168:169]
	v_cvt_pk_bf16_f32 v134, v64, v65
	v_lshlrev_b32_e32 v66, 16, v135
	v_and_b32_e32 v67, 0xffff0000, v135
	v_pk_mul_f32 v[66:67], v[66:67], v[44:45]
	v_pk_fma_f32 v[66:67], v[66:67], v[8:9], v[170:171]
	v_cvt_pk_bf16_f32 v135, v66, v67
	v_lshlrev_b32_e32 v60, 16, v136
	v_and_b32_e32 v61, 0xffff0000, v136
	v_pk_mul_f32 v[60:61], v[60:61], v[44:45]
	v_pk_fma_f32 v[60:61], v[60:61], v[10:11], v[172:173]
	v_cvt_pk_bf16_f32 v136, v60, v61
	v_lshlrev_b32_e32 v62, 16, v137
	v_and_b32_e32 v63, 0xffff0000, v137
	v_pk_mul_f32 v[62:63], v[62:63], v[44:45]
	v_pk_fma_f32 v[62:63], v[62:63], v[12:13], v[174:175]
	v_cvt_pk_bf16_f32 v137, v62, v63
	v_lshlrev_b32_e32 v64, 16, v138
	v_and_b32_e32 v65, 0xffff0000, v138
	v_pk_mul_f32 v[64:65], v[64:65], v[44:45]
	v_pk_fma_f32 v[64:65], v[64:65], v[14:15], v[176:177]
	v_cvt_pk_bf16_f32 v138, v64, v65
	v_lshlrev_b32_e32 v66, 16, v139
	v_and_b32_e32 v67, 0xffff0000, v139
	v_pk_mul_f32 v[66:67], v[66:67], v[44:45]
	v_pk_fma_f32 v[66:67], v[66:67], v[16:17], v[178:179]
	v_cvt_pk_bf16_f32 v139, v66, v67
	v_lshlrev_b32_e32 v60, 16, v140
	v_and_b32_e32 v61, 0xffff0000, v140
	v_pk_mul_f32 v[60:61], v[60:61], v[44:45]
	v_pk_fma_f32 v[60:61], v[60:61], v[18:19], v[180:181]
	v_cvt_pk_bf16_f32 v140, v60, v61
	v_lshlrev_b32_e32 v62, 16, v141
	v_and_b32_e32 v63, 0xffff0000, v141
	v_pk_mul_f32 v[62:63], v[62:63], v[44:45]
	v_pk_fma_f32 v[62:63], v[62:63], v[20:21], v[182:183]
	v_cvt_pk_bf16_f32 v141, v62, v63
	v_lshlrev_b32_e32 v64, 16, v142
	v_and_b32_e32 v65, 0xffff0000, v142
	v_pk_mul_f32 v[64:65], v[64:65], v[44:45]
	v_pk_fma_f32 v[64:65], v[64:65], v[22:23], v[184:185]
	v_cvt_pk_bf16_f32 v142, v64, v65
	v_lshlrev_b32_e32 v66, 16, v143
	v_and_b32_e32 v67, 0xffff0000, v143
	v_pk_mul_f32 v[66:67], v[66:67], v[44:45]
	v_pk_fma_f32 v[66:67], v[66:67], v[24:25], v[186:187]
	v_cvt_pk_bf16_f32 v143, v66, v67
	v_lshlrev_b32_e32 v60, 16, v144
	v_and_b32_e32 v61, 0xffff0000, v144
	v_pk_mul_f32 v[60:61], v[60:61], v[44:45]
	v_pk_fma_f32 v[60:61], v[60:61], v[26:27], v[188:189]
	v_cvt_pk_bf16_f32 v144, v60, v61
	v_lshlrev_b32_e32 v62, 16, v145
	v_and_b32_e32 v63, 0xffff0000, v145
	v_pk_mul_f32 v[62:63], v[62:63], v[44:45]
	v_pk_fma_f32 v[62:63], v[62:63], v[28:29], v[190:191]
	v_cvt_pk_bf16_f32 v145, v62, v63
	v_lshlrev_b32_e32 v64, 16, v146
	v_and_b32_e32 v65, 0xffff0000, v146
	v_pk_mul_f32 v[64:65], v[64:65], v[44:45]
	v_pk_fma_f32 v[64:65], v[64:65], v[30:31], v[192:193]
	v_cvt_pk_bf16_f32 v146, v64, v65
	v_lshlrev_b32_e32 v66, 16, v147
	v_and_b32_e32 v67, 0xffff0000, v147
	v_pk_mul_f32 v[66:67], v[66:67], v[44:45]
	v_pk_fma_f32 v[66:67], v[66:67], v[32:33], v[194:195]
	v_cvt_pk_bf16_f32 v147, v66, v67
	global_store_dwordx4 v39, v[132:135], s[20:21]
	global_store_dwordx4 v39, v[136:139], s[20:21] offset:1024
	global_store_dwordx4 v39, v[140:143], s[20:21] offset:2048
	global_store_dwordx4 v39, v[144:147], s[20:21] offset:3072
	s_add_u32 s20, s20, 0x1000
	s_addc_u32 s21, s21, 0
	s_waitcnt vmcnt(12)
	v_lshlrev_b32_e32 v60, 16, v148
	v_and_b32_e32 v61, 0xffff0000, v148
	v_pk_mul_f32 v[42:43], v[60:61], v[60:61]
	v_lshlrev_b32_e32 v62, 16, v149
	v_and_b32_e32 v63, 0xffff0000, v149
	v_pk_fma_f32 v[42:43], v[62:63], v[62:63], v[42:43]
	v_lshlrev_b32_e32 v64, 16, v150
	v_and_b32_e32 v65, 0xffff0000, v150
	v_pk_fma_f32 v[42:43], v[64:65], v[64:65], v[42:43]
	v_lshlrev_b32_e32 v66, 16, v151
	v_and_b32_e32 v67, 0xffff0000, v151
	v_pk_fma_f32 v[42:43], v[66:67], v[66:67], v[42:43]
	v_lshlrev_b32_e32 v60, 16, v152
	v_and_b32_e32 v61, 0xffff0000, v152
	v_pk_fma_f32 v[42:43], v[60:61], v[60:61], v[42:43]
	v_lshlrev_b32_e32 v62, 16, v153
	v_and_b32_e32 v63, 0xffff0000, v153
	v_pk_fma_f32 v[42:43], v[62:63], v[62:63], v[42:43]
	v_lshlrev_b32_e32 v64, 16, v154
	v_and_b32_e32 v65, 0xffff0000, v154
	v_pk_fma_f32 v[42:43], v[64:65], v[64:65], v[42:43]
	v_lshlrev_b32_e32 v66, 16, v155
	v_and_b32_e32 v67, 0xffff0000, v155
	v_pk_fma_f32 v[42:43], v[66:67], v[66:67], v[42:43]
	v_lshlrev_b32_e32 v60, 16, v156
	v_and_b32_e32 v61, 0xffff0000, v156
	v_pk_fma_f32 v[42:43], v[60:61], v[60:61], v[42:43]
	v_lshlrev_b32_e32 v62, 16, v157
	v_and_b32_e32 v63, 0xffff0000, v157
	v_pk_fma_f32 v[42:43], v[62:63], v[62:63], v[42:43]
	v_lshlrev_b32_e32 v64, 16, v158
	v_and_b32_e32 v65, 0xffff0000, v158
	v_pk_fma_f32 v[42:43], v[64:65], v[64:65], v[42:43]
	v_lshlrev_b32_e32 v66, 16, v159
	v_and_b32_e32 v67, 0xffff0000, v159
	v_pk_fma_f32 v[42:43], v[66:67], v[66:67], v[42:43]
	v_lshlrev_b32_e32 v60, 16, v160
	v_and_b32_e32 v61, 0xffff0000, v160
	v_pk_fma_f32 v[42:43], v[60:61], v[60:61], v[42:43]
	v_lshlrev_b32_e32 v62, 16, v161
	v_and_b32_e32 v63, 0xffff0000, v161
	v_pk_fma_f32 v[42:43], v[62:63], v[62:63], v[42:43]
	v_lshlrev_b32_e32 v64, 16, v162
	v_and_b32_e32 v65, 0xffff0000, v162
	v_pk_fma_f32 v[42:43], v[64:65], v[64:65], v[42:43]
	v_lshlrev_b32_e32 v66, 16, v163
	v_and_b32_e32 v67, 0xffff0000, v163
	v_pk_fma_f32 v[42:43], v[66:67], v[66:67], v[42:43]
	v_add_f32_e32 v42, v42, v43
	s_nop 1
	v_add_f32_dpp v42, v42, v42 quad_perm:[1,0,3,2] row_mask:0xf bank_mask:0xf
	s_nop 1
	v_add_f32_dpp v42, v42, v42 quad_perm:[2,3,0,1] row_mask:0xf bank_mask:0xf
	s_nop 1
	v_add_f32_dpp v42, v42, v42 row_half_mirror row_mask:0xf bank_mask:0xf
	s_nop 1
	v_add_f32_dpp v42, v42, v42 row_mirror row_mask:0xf bank_mask:0xf
	s_nop 1
	v_add_f32_dpp v42, v42, v42 row_bcast:15 row_mask:0xa bank_mask:0xf
	s_nop 1
	v_add_f32_dpp v42, v42, v42 row_bcast:31 row_mask:0xc bank_mask:0xf
	s_nop 1
	v_readlane_b32 s100, v42, 63
	s_nop 3
	v_mov_b32_e32 v44, s100
	v_fma_f32 v44, v44, v47, v224
	v_rsq_f32_e32 v45, v44
	s_nop 0
	v_mul_f32_e32 v46, v44, v45
	v_mul_f32_e32 v46, v46, v45
	v_fmaak_f32 v46, -0.5, v46, 0x3fc00000
	v_mul_f32_e32 v44, v45, v46
	v_mov_b32_e32 v45, v44
	v_lshlrev_b32_e32 v60, 16, v148
	v_and_b32_e32 v61, 0xffff0000, v148
	v_pk_mul_f32 v[60:61], v[60:61], v[44:45]
	v_pk_fma_f32 v[60:61], v[60:61], v[2:3], v[164:165]
	v_cvt_pk_bf16_f32 v148, v60, v61
	v_lshlrev_b32_e32 v62, 16, v149
	v_and_b32_e32 v63, 0xffff0000, v149
	v_pk_mul_f32 v[62:63], v[62:63], v[44:45]
	v_pk_fma_f32 v[62:63], v[62:63], v[4:5], v[166:167]
	v_cvt_pk_bf16_f32 v149, v62, v63
	v_lshlrev_b32_e32 v64, 16, v150
	v_and_b32_e32 v65, 0xffff0000, v150
	v_pk_mul_f32 v[64:65], v[64:65], v[44:45]
	v_pk_fma_f32 v[64:65], v[64:65], v[6:7], v[168:169]
	v_cvt_pk_bf16_f32 v150, v64, v65
	v_lshlrev_b32_e32 v66, 16, v151
	v_and_b32_e32 v67, 0xffff0000, v151
	v_pk_mul_f32 v[66:67], v[66:67], v[44:45]
	v_pk_fma_f32 v[66:67], v[66:67], v[8:9], v[170:171]
	v_cvt_pk_bf16_f32 v151, v66, v67
	v_lshlrev_b32_e32 v60, 16, v152
	v_and_b32_e32 v61, 0xffff0000, v152
	v_pk_mul_f32 v[60:61], v[60:61], v[44:45]
	v_pk_fma_f32 v[60:61], v[60:61], v[10:11], v[172:173]
	v_cvt_pk_bf16_f32 v152, v60, v61
	v_lshlrev_b32_e32 v62, 16, v153
	v_and_b32_e32 v63, 0xffff0000, v153
	v_pk_mul_f32 v[62:63], v[62:63], v[44:45]
	v_pk_fma_f32 v[62:63], v[62:63], v[12:13], v[174:175]
	v_cvt_pk_bf16_f32 v153, v62, v63
	v_lshlrev_b32_e32 v64, 16, v154
	v_and_b32_e32 v65, 0xffff0000, v154
	v_pk_mul_f32 v[64:65], v[64:65], v[44:45]
	v_pk_fma_f32 v[64:65], v[64:65], v[14:15], v[176:177]
	v_cvt_pk_bf16_f32 v154, v64, v65
	v_lshlrev_b32_e32 v66, 16, v155
	v_and_b32_e32 v67, 0xffff0000, v155
	v_pk_mul_f32 v[66:67], v[66:67], v[44:45]
	v_pk_fma_f32 v[66:67], v[66:67], v[16:17], v[178:179]
	v_cvt_pk_bf16_f32 v155, v66, v67
	v_lshlrev_b32_e32 v60, 16, v156
	v_and_b32_e32 v61, 0xffff0000, v156
	v_pk_mul_f32 v[60:61], v[60:61], v[44:45]
	v_pk_fma_f32 v[60:61], v[60:61], v[18:19], v[180:181]
	v_cvt_pk_bf16_f32 v156, v60, v61
	v_lshlrev_b32_e32 v62, 16, v157
	v_and_b32_e32 v63, 0xffff0000, v157
	v_pk_mul_f32 v[62:63], v[62:63], v[44:45]
	v_pk_fma_f32 v[62:63], v[62:63], v[20:21], v[182:183]
	v_cvt_pk_bf16_f32 v157, v62, v63
	v_lshlrev_b32_e32 v64, 16, v158
	v_and_b32_e32 v65, 0xffff0000, v158
	v_pk_mul_f32 v[64:65], v[64:65], v[44:45]
	v_pk_fma_f32 v[64:65], v[64:65], v[22:23], v[184:185]
	v_cvt_pk_bf16_f32 v158, v64, v65
	v_lshlrev_b32_e32 v66, 16, v159
	v_and_b32_e32 v67, 0xffff0000, v159
	v_pk_mul_f32 v[66:67], v[66:67], v[44:45]
	v_pk_fma_f32 v[66:67], v[66:67], v[24:25], v[186:187]
	v_cvt_pk_bf16_f32 v159, v66, v67
	v_lshlrev_b32_e32 v60, 16, v160
	v_and_b32_e32 v61, 0xffff0000, v160
	v_pk_mul_f32 v[60:61], v[60:61], v[44:45]
	v_pk_fma_f32 v[60:61], v[60:61], v[26:27], v[188:189]
	v_cvt_pk_bf16_f32 v160, v60, v61
	v_lshlrev_b32_e32 v62, 16, v161
	v_and_b32_e32 v63, 0xffff0000, v161
	v_pk_mul_f32 v[62:63], v[62:63], v[44:45]
	v_pk_fma_f32 v[62:63], v[62:63], v[28:29], v[190:191]
	v_cvt_pk_bf16_f32 v161, v62, v63
	v_lshlrev_b32_e32 v64, 16, v162
	v_and_b32_e32 v65, 0xffff0000, v162
	v_pk_mul_f32 v[64:65], v[64:65], v[44:45]
	v_pk_fma_f32 v[64:65], v[64:65], v[30:31], v[192:193]
	v_cvt_pk_bf16_f32 v162, v64, v65
	v_lshlrev_b32_e32 v66, 16, v163
	v_and_b32_e32 v67, 0xffff0000, v163
	v_pk_mul_f32 v[66:67], v[66:67], v[44:45]
	v_pk_fma_f32 v[66:67], v[66:67], v[32:33], v[194:195]
	v_cvt_pk_bf16_f32 v163, v66, v67
	global_store_dwordx4 v39, v[148:151], s[20:21]
	global_store_dwordx4 v39, v[152:155], s[20:21] offset:1024
	global_store_dwordx4 v39, v[156:159], s[20:21] offset:2048
	global_store_dwordx4 v39, v[160:163], s[20:21] offset:3072
	s_add_u32 s20, s20, 0x1000
	s_addc_u32 s21, s21, 0

.LBB0_898:
	s_andn2_b64 vcc, exec, s[4:5]
	s_cbranch_vccnz .LBB0_962
	v_readlane_b32 s8, v253, 2
	s_mov_b64 s[4:5], s[96:97]
	s_mov_b64 s[36:37], s[96:97]
	s_mov_b64 s[20:21], s[96:97]
	v_mov_b32_e32 v2, v0
	v_readlane_b32 s9, v253, 3
	s_load_dword s6, s[8:9], 0x0
	v_readfirstlane_b32 s7, v2
	s_ashr_i32 s10, s7, 6
	v_readlane_b32 s7, v254, 16
	s_add_i32 s7, s10, s7
	s_cmp_ge_i32 s7, s81
	s_cbranch_scc1 .LBB0_908
	s_load_dwordx2 s[8:9], s[36:37], 0xb8
	s_waitcnt lgkmcnt(0)
	s_mul_i32 s52, s80, 0x5000
	s_lshl_b64 s[36:37], s[52:53], 2
	s_load_dwordx2 s[20:21], s[20:21], 0xb8
	s_mul_i32 s52, s80, 0xf000
	s_add_u32 s8, s8, s36
	s_addc_u32 s9, s9, s37
	s_add_u32 s8, s8, 0x195de000
	s_addc_u32 s9, s9, 0
	s_cmp_lg_u32 s80, 3
	s_cselect_b64 s[36:37], -1, 0
	s_cmp_eq_u32 s80, 0
	s_load_dwordx2 s[40:41], s[4:5], 0xb8
	s_cselect_b64 s[38:39], -1, 0
	s_lshl_b32 s42, s6, 3
	s_lshl_b64 s[44:45], s[52:53], 2
	s_waitcnt lgkmcnt(0)
	s_add_u32 s11, s20, s44
	s_addc_u32 s12, s21, s45
	v_and_b32_e32 v3, 63, v2
	s_add_u32 s54, s11, 0x194e6000
	v_lshlrev_b32_e32 v98, 5, v3
	s_addc_u32 s55, s12, 0
	v_lshl_add_u64 v[4:5], s[40:41], 0, v[98:99]
	s_mov_b64 s[12:13], 0x3bce8000
	v_lshl_add_u64 v[34:35], v[4:5], 0, s[12:13]
	s_ashr_i32 s11, s10, 31
	v_readlane_b32 s12, v254, 16
	s_add_u32 s10, s12, s10
	v_readlane_b32 s12, v254, 58
	s_addc_u32 s11, s12, s11
	s_lshl_b64 s[10:11], s[10:11], 12
	s_add_u32 s10, s40, s10
	v_lshlrev_b32_e32 v4, 3, v3
	v_lshlrev_b32_e32 v98, 4, v3
	s_addc_u32 s11, s41, s11
	v_lshlrev_b32_e32 v2, 1, v3
	v_or_b32_e32 v6, 0x400, v4
	v_or_b32_e32 v8, 0x600, v4
	v_lshl_add_u64 v[10:11], s[10:11], 0, v[98:99]
	s_mov_b64 s[10:11], 0x1da24c00
	s_ashr_i32 s43, s42, 31
	v_lshl_add_u64 v[36:37], v[10:11], 0, s[10:11]
	s_lshl_b64 s[44:45], s[42:43], 12
	v_lshlrev_b32_e32 v98, 4, v2
	v_lshlrev_b32_e32 v48, 2, v4
	v_lshlrev_b32_e32 v49, 2, v6
	v_lshlrev_b32_e32 v50, 2, v8
	s_mov_b32 s101, 0
	s_cmp_lg_u32 s6, 0x100
	s_cbranch_scc1 .Lnf2_skip
	s_mov_b32 s101, 1
	s_load_dwordx2 s[40:41], s[4:5], 0xb8
	v_and_b32_e32 v38, 63, v0
	v_lshlrev_b32_e32 v39, 4, v38
	v_lshlrev_b32_e32 v40, 5, v38
	s_lshr_b32 s20, s7, 3
	s_and_b32 s21, s20, 7
	s_lshl_b32 s21, s21, 5
	s_lshr_b32 s20, s20, 3
	s_or_b32 s20, s20, s21
	s_lshl_b32 s20, s20, 3
	s_and_b32 s21, s7, 7
	s_or_b32 s49, s20, s21
	s_lshl_b32 s10, s49, 15
	s_lshr_b32 s48, s49, 9
	s_lshl_b32 s20, s48, 13
	s_mul_i32 s49, s48, 0xc000
	s_waitcnt lgkmcnt(0)
	s_add_u32 s10, s40, s10
	s_addc_u32 s11, s41, 0
	s_add_u32 s10, s10, 0x19624000
	s_addc_u32 s11, s11, 0
	s_add_u32 s40, s8, s20
	s_addc_u32 s41, s9, 0
	s_add_u32 s48, s54, s49
	s_addc_u32 s49, s55, 0
	s_add_u32 s20, s10, 0x4400000
	s_addc_u32 s21, s11, 0
	global_load_dwordx4 v[100:103], v39, s[10:11]
	global_load_dwordx4 v[104:107], v39, s[10:11] offset:1024
	global_load_dwordx4 v[108:111], v39, s[10:11] offset:2048
	global_load_dwordx4 v[112:115], v39, s[10:11] offset:3072
	s_add_u32 s10, s10, 0x1000
	s_addc_u32 s11, s11, 0
	global_load_dwordx4 v[2:5], v40, s[40:41]
	global_load_dwordx4 v[6:9], v40, s[40:41] offset:16
	global_load_dwordx4 v[10:13], v40, s[40:41] offset:2048
	global_load_dwordx4 v[14:17], v40, s[40:41] offset:2064
	s_add_u32 s40, s40, 0x1000
	s_addc_u32 s41, s41, 0
	global_load_dwordx4 v[18:21], v40, s[40:41]
	global_load_dwordx4 v[22:25], v40, s[40:41] offset:16
	global_load_dwordx4 v[26:29], v40, s[40:41] offset:2048
	global_load_dwordx4 v[30:33], v40, s[40:41] offset:2064
	global_load_dwordx4 v[164:167], v40, s[48:49]
	global_load_dwordx4 v[168:171], v40, s[48:49] offset:16
	global_load_dwordx4 v[172:175], v40, s[48:49] offset:2048
	global_load_dwordx4 v[176:179], v40, s[48:49] offset:2064
	s_add_u32 s48, s48, 0x1000
	s_addc_u32 s49, s49, 0
	global_load_dwordx4 v[180:183], v40, s[48:49]
	global_load_dwordx4 v[184:187], v40, s[48:49] offset:16
	global_load_dwordx4 v[188:191], v40, s[48:49] offset:2048
	global_load_dwordx4 v[192:195], v40, s[48:49] offset:2064
	global_load_dwordx4 v[116:119], v39, s[10:11]
	global_load_dwordx4 v[120:123], v39, s[10:11] offset:1024
	global_load_dwordx4 v[124:127], v39, s[10:11] offset:2048
	global_load_dwordx4 v[128:131], v39, s[10:11] offset:3072
	s_add_u32 s10, s10, 0x1000
	s_addc_u32 s11, s11, 0
	global_load_dwordx4 v[132:135], v39, s[10:11]
	global_load_dwordx4 v[136:139], v39, s[10:11] offset:1024
	global_load_dwordx4 v[140:143], v39, s[10:11] offset:2048
	global_load_dwordx4 v[144:147], v39, s[10:11] offset:3072
	s_add_u32 s10, s10, 0x1000
	s_addc_u32 s11, s11, 0
	global_load_dwordx4 v[148:151], v39, s[10:11]
	global_load_dwordx4 v[152:155], v39, s[10:11] offset:1024
	global_load_dwordx4 v[156:159], v39, s[10:11] offset:2048
	global_load_dwordx4 v[160:163], v39, s[10:11] offset:3072
	s_add_u32 s10, s10, 0x1000
	s_addc_u32 s11, s11, 0
	v_mov_b32_e32 v47, 0x3a000000
	s_waitcnt vmcnt(28)
	v_lshlrev_b32_e32 v60, 16, v100
	v_and_b32_e32 v61, 0xffff0000, v100
	v_pk_mul_f32 v[42:43], v[60:61], v[60:61]
	v_lshlrev_b32_e32 v62, 16, v101
	v_and_b32_e32 v63, 0xffff0000, v101
	v_pk_fma_f32 v[42:43], v[62:63], v[62:63], v[42:43]
	v_lshlrev_b32_e32 v64, 16, v102
	v_and_b32_e32 v65, 0xffff0000, v102
	v_pk_fma_f32 v[42:43], v[64:65], v[64:65], v[42:43]
	v_lshlrev_b32_e32 v66, 16, v103
	v_and_b32_e32 v67, 0xffff0000, v103
	v_pk_fma_f32 v[42:43], v[66:67], v[66:67], v[42:43]
	v_lshlrev_b32_e32 v60, 16, v104
	v_and_b32_e32 v61, 0xffff0000, v104
	v_pk_fma_f32 v[42:43], v[60:61], v[60:61], v[42:43]
	v_lshlrev_b32_e32 v62, 16, v105
	v_and_b32_e32 v63, 0xffff0000, v105
	v_pk_fma_f32 v[42:43], v[62:63], v[62:63], v[42:43]
	v_lshlrev_b32_e32 v64, 16, v106
	v_and_b32_e32 v65, 0xffff0000, v106
	v_pk_fma_f32 v[42:43], v[64:65], v[64:65], v[42:43]
	v_lshlrev_b32_e32 v66, 16, v107
	v_and_b32_e32 v67, 0xffff0000, v107
	v_pk_fma_f32 v[42:43], v[66:67], v[66:67], v[42:43]
	v_lshlrev_b32_e32 v60, 16, v108
	v_and_b32_e32 v61, 0xffff0000, v108
	v_pk_fma_f32 v[42:43], v[60:61], v[60:61], v[42:43]
	v_lshlrev_b32_e32 v62, 16, v109
	v_and_b32_e32 v63, 0xffff0000, v109
	v_pk_fma_f32 v[42:43], v[62:63], v[62:63], v[42:43]
	v_lshlrev_b32_e32 v64, 16, v110
	v_and_b32_e32 v65, 0xffff0000, v110
	v_pk_fma_f32 v[42:43], v[64:65], v[64:65], v[42:43]
	v_lshlrev_b32_e32 v66, 16, v111
	v_and_b32_e32 v67, 0xffff0000, v111
	v_pk_fma_f32 v[42:43], v[66:67], v[66:67], v[42:43]
	v_lshlrev_b32_e32 v60, 16, v112
	v_and_b32_e32 v61, 0xffff0000, v112
	v_pk_fma_f32 v[42:43], v[60:61], v[60:61], v[42:43]
	v_lshlrev_b32_e32 v62, 16, v113
	v_and_b32_e32 v63, 0xffff0000, v113
	v_pk_fma_f32 v[42:43], v[62:63], v[62:63], v[42:43]
	v_lshlrev_b32_e32 v64, 16, v114
	v_and_b32_e32 v65, 0xffff0000, v114
	v_pk_fma_f32 v[42:43], v[64:65], v[64:65], v[42:43]
	v_lshlrev_b32_e32 v66, 16, v115
	v_and_b32_e32 v67, 0xffff0000, v115
	v_pk_fma_f32 v[42:43], v[66:67], v[66:67], v[42:43]
	v_add_f32_e32 v42, v42, v43
	s_nop 1
	v_add_f32_dpp v42, v42, v42 quad_perm:[1,0,3,2] row_mask:0xf bank_mask:0xf
	s_nop 1
	v_add_f32_dpp v42, v42, v42 quad_perm:[2,3,0,1] row_mask:0xf bank_mask:0xf
	s_nop 1
	v_add_f32_dpp v42, v42, v42 row_half_mirror row_mask:0xf bank_mask:0xf
	s_nop 1
	v_add_f32_dpp v42, v42, v42 row_mirror row_mask:0xf bank_mask:0xf
	s_nop 1
	v_add_f32_dpp v42, v42, v42 row_bcast:15 row_mask:0xa bank_mask:0xf
	s_nop 1
	v_add_f32_dpp v42, v42, v42 row_bcast:31 row_mask:0xc bank_mask:0xf
	s_nop 1
	v_readlane_b32 s100, v42, 63
	s_nop 3
	v_mov_b32_e32 v44, s100
	v_fma_f32 v44, v44, v47, v224
	v_rsq_f32_e32 v45, v44
	s_nop 0
	v_mul_f32_e32 v46, v44, v45
	v_mul_f32_e32 v46, v46, v45
	v_fmaak_f32 v46, -0.5, v46, 0x3fc00000
	v_mul_f32_e32 v44, v45, v46
	v_mov_b32_e32 v45, v44
	s_waitcnt vmcnt(12)
	v_lshlrev_b32_e32 v60, 16, v100
	v_and_b32_e32 v61, 0xffff0000, v100
	v_pk_mul_f32 v[60:61], v[60:61], v[44:45]
	v_pk_fma_f32 v[60:61], v[60:61], v[2:3], v[164:165]
	v_cvt_pk_bf16_f32 v100, v60, v61
	v_lshlrev_b32_e32 v62, 16, v101
	v_and_b32_e32 v63, 0xffff0000, v101
	v_pk_mul_f32 v[62:63], v[62:63], v[44:45]
	v_pk_fma_f32 v[62:63], v[62:63], v[4:5], v[166:167]
	v_cvt_pk_bf16_f32 v101, v62, v63
	v_lshlrev_b32_e32 v64, 16, v102
	v_and_b32_e32 v65, 0xffff0000, v102
	v_pk_mul_f32 v[64:65], v[64:65], v[44:45]
	v_pk_fma_f32 v[64:65], v[64:65], v[6:7], v[168:169]
	v_cvt_pk_bf16_f32 v102, v64, v65
	v_lshlrev_b32_e32 v66, 16, v103
	v_and_b32_e32 v67, 0xffff0000, v103
	v_pk_mul_f32 v[66:67], v[66:67], v[44:45]
	v_pk_fma_f32 v[66:67], v[66:67], v[8:9], v[170:171]
	v_cvt_pk_bf16_f32 v103, v66, v67
	v_lshlrev_b32_e32 v60, 16, v104
	v_and_b32_e32 v61, 0xffff0000, v104
	v_pk_mul_f32 v[60:61], v[60:61], v[44:45]
	v_pk_fma_f32 v[60:61], v[60:61], v[10:11], v[172:173]
	v_cvt_pk_bf16_f32 v104, v60, v61
	v_lshlrev_b32_e32 v62, 16, v105
	v_and_b32_e32 v63, 0xffff0000, v105
	v_pk_mul_f32 v[62:63], v[62:63], v[44:45]
	v_pk_fma_f32 v[62:63], v[62:63], v[12:13], v[174:175]
	v_cvt_pk_bf16_f32 v105, v62, v63
	v_lshlrev_b32_e32 v64, 16, v106
	v_and_b32_e32 v65, 0xffff0000, v106
	v_pk_mul_f32 v[64:65], v[64:65], v[44:45]
	v_pk_fma_f32 v[64:65], v[64:65], v[14:15], v[176:177]
	v_cvt_pk_bf16_f32 v106, v64, v65
	v_lshlrev_b32_e32 v66, 16, v107
	v_and_b32_e32 v67, 0xffff0000, v107
	v_pk_mul_f32 v[66:67], v[66:67], v[44:45]
	v_pk_fma_f32 v[66:67], v[66:67], v[16:17], v[178:179]
	v_cvt_pk_bf16_f32 v107, v66, v67
	v_lshlrev_b32_e32 v60, 16, v108
	v_and_b32_e32 v61, 0xffff0000, v108
	v_pk_mul_f32 v[60:61], v[60:61], v[44:45]
	v_pk_fma_f32 v[60:61], v[60:61], v[18:19], v[180:181]
	v_cvt_pk_bf16_f32 v108, v60, v61
	v_lshlrev_b32_e32 v62, 16, v109
	v_and_b32_e32 v63, 0xffff0000, v109
	v_pk_mul_f32 v[62:63], v[62:63], v[44:45]
	v_pk_fma_f32 v[62:63], v[62:63], v[20:21], v[182:183]
	v_cvt_pk_bf16_f32 v109, v62, v63
	v_lshlrev_b32_e32 v64, 16, v110
	v_and_b32_e32 v65, 0xffff0000, v110
	v_pk_mul_f32 v[64:65], v[64:65], v[44:45]
	v_pk_fma_f32 v[64:65], v[64:65], v[22:23], v[184:185]
	v_cvt_pk_bf16_f32 v110, v64, v65
	v_lshlrev_b32_e32 v66, 16, v111
	v_and_b32_e32 v67, 0xffff0000, v111
	v_pk_mul_f32 v[66:67], v[66:67], v[44:45]
	v_pk_fma_f32 v[66:67], v[66:67], v[24:25], v[186:187]
	v_cvt_pk_bf16_f32 v111, v66, v67
	v_lshlrev_b32_e32 v60, 16, v112
	v_and_b32_e32 v61, 0xffff0000, v112
	v_pk_mul_f32 v[60:61], v[60:61], v[44:45]
	v_pk_fma_f32 v[60:61], v[60:61], v[26:27], v[188:189]
	v_cvt_pk_bf16_f32 v112, v60, v61
	v_lshlrev_b32_e32 v62, 16, v113
	v_and_b32_e32 v63, 0xffff0000, v113
	v_pk_mul_f32 v[62:63], v[62:63], v[44:45]
	v_pk_fma_f32 v[62:63], v[62:63], v[28:29], v[190:191]
	v_cvt_pk_bf16_f32 v113, v62, v63
	v_lshlrev_b32_e32 v64, 16, v114
	v_and_b32_e32 v65, 0xffff0000, v114
	v_pk_mul_f32 v[64:65], v[64:65], v[44:45]
	v_pk_fma_f32 v[64:65], v[64:65], v[30:31], v[192:193]
	v_cvt_pk_bf16_f32 v114, v64, v65
	v_lshlrev_b32_e32 v66, 16, v115
	v_and_b32_e32 v67, 0xffff0000, v115
	v_pk_mul_f32 v[66:67], v[66:67], v[44:45]
	v_pk_fma_f32 v[66:67], v[66:67], v[32:33], v[194:195]
	v_cvt_pk_bf16_f32 v115, v66, v67
	global_store_dwordx4 v39, v[100:103], s[20:21]
	global_store_dwordx4 v39, v[104:107], s[20:21] offset:1024
	global_store_dwordx4 v39, v[108:111], s[20:21] offset:2048
	global_store_dwordx4 v39, v[112:115], s[20:21] offset:3072
	s_add_u32 s20, s20, 0x1000
	s_addc_u32 s21, s21, 0
	global_load_dwordx4 v[100:103], v39, s[10:11]
	global_load_dwordx4 v[104:107], v39, s[10:11] offset:1024
	global_load_dwordx4 v[108:111], v39, s[10:11] offset:2048
	global_load_dwordx4 v[112:115], v39, s[10:11] offset:3072
	s_add_u32 s10, s10, 0x1000
	s_addc_u32 s11, s11, 0
	s_waitcnt vmcnt(16)
	v_lshlrev_b32_e32 v60, 16, v116
	v_and_b32_e32 v61, 0xffff0000, v116
	v_pk_mul_f32 v[42:43], v[60:61], v[60:61]
	v_lshlrev_b32_e32 v62, 16, v117
	v_and_b32_e32 v63, 0xffff0000, v117
	v_pk_fma_f32 v[42:43], v[62:63], v[62:63], v[42:43]
	v_lshlrev_b32_e32 v64, 16, v118
	v_and_b32_e32 v65, 0xffff0000, v118
	v_pk_fma_f32 v[42:43], v[64:65], v[64:65], v[42:43]
	v_lshlrev_b32_e32 v66, 16, v119
	v_and_b32_e32 v67, 0xffff0000, v119
	v_pk_fma_f32 v[42:43], v[66:67], v[66:67], v[42:43]
	v_lshlrev_b32_e32 v60, 16, v120
	v_and_b32_e32 v61, 0xffff0000, v120
	v_pk_fma_f32 v[42:43], v[60:61], v[60:61], v[42:43]
	v_lshlrev_b32_e32 v62, 16, v121
	v_and_b32_e32 v63, 0xffff0000, v121
	v_pk_fma_f32 v[42:43], v[62:63], v[62:63], v[42:43]
	v_lshlrev_b32_e32 v64, 16, v122
	v_and_b32_e32 v65, 0xffff0000, v122
	v_pk_fma_f32 v[42:43], v[64:65], v[64:65], v[42:43]
	v_lshlrev_b32_e32 v66, 16, v123
	v_and_b32_e32 v67, 0xffff0000, v123
	v_pk_fma_f32 v[42:43], v[66:67], v[66:67], v[42:43]
	v_lshlrev_b32_e32 v60, 16, v124
	v_and_b32_e32 v61, 0xffff0000, v124
	v_pk_fma_f32 v[42:43], v[60:61], v[60:61], v[42:43]
	v_lshlrev_b32_e32 v62, 16, v125
	v_and_b32_e32 v63, 0xffff0000, v125
	v_pk_fma_f32 v[42:43], v[62:63], v[62:63], v[42:43]
	v_lshlrev_b32_e32 v64, 16, v126
	v_and_b32_e32 v65, 0xffff0000, v126
	v_pk_fma_f32 v[42:43], v[64:65], v[64:65], v[42:43]
	v_lshlrev_b32_e32 v66, 16, v127
	v_and_b32_e32 v67, 0xffff0000, v127
	v_pk_fma_f32 v[42:43], v[66:67], v[66:67], v[42:43]
	v_lshlrev_b32_e32 v60, 16, v128
	v_and_b32_e32 v61, 0xffff0000, v128
	v_pk_fma_f32 v[42:43], v[60:61], v[60:61], v[42:43]
	v_lshlrev_b32_e32 v62, 16, v129
	v_and_b32_e32 v63, 0xffff0000, v129
	v_pk_fma_f32 v[42:43], v[62:63], v[62:63], v[42:43]
	v_lshlrev_b32_e32 v64, 16, v130
	v_and_b32_e32 v65, 0xffff0000, v130
	v_pk_fma_f32 v[42:43], v[64:65], v[64:65], v[42:43]
	v_lshlrev_b32_e32 v66, 16, v131
	v_and_b32_e32 v67, 0xffff0000, v131
	v_pk_fma_f32 v[42:43], v[66:67], v[66:67], v[42:43]
	v_add_f32_e32 v42, v42, v43
	s_nop 1
	v_add_f32_dpp v42, v42, v42 quad_perm:[1,0,3,2] row_mask:0xf bank_mask:0xf
	s_nop 1
	v_add_f32_dpp v42, v42, v42 quad_perm:[2,3,0,1] row_mask:0xf bank_mask:0xf
	s_nop 1
	v_add_f32_dpp v42, v42, v42 row_half_mirror row_mask:0xf bank_mask:0xf
	s_nop 1
	v_add_f32_dpp v42, v42, v42 row_mirror row_mask:0xf bank_mask:0xf
	s_nop 1
	v_add_f32_dpp v42, v42, v42 row_bcast:15 row_mask:0xa bank_mask:0xf
	s_nop 1
	v_add_f32_dpp v42, v42, v42 row_bcast:31 row_mask:0xc bank_mask:0xf
	s_nop 1
	v_readlane_b32 s100, v42, 63
	s_nop 3
	v_mov_b32_e32 v44, s100
	v_fma_f32 v44, v44, v47, v224
	v_rsq_f32_e32 v45, v44
	s_nop 0
	v_mul_f32_e32 v46, v44, v45
	v_mul_f32_e32 v46, v46, v45
	v_fmaak_f32 v46, -0.5, v46, 0x3fc00000
	v_mul_f32_e32 v44, v45, v46
	v_mov_b32_e32 v45, v44
	v_lshlrev_b32_e32 v60, 16, v116
	v_and_b32_e32 v61, 0xffff0000, v116
	v_pk_mul_f32 v[60:61], v[60:61], v[44:45]
	v_pk_fma_f32 v[60:61], v[60:61], v[2:3], v[164:165]
	v_cvt_pk_bf16_f32 v116, v60, v61
	v_lshlrev_b32_e32 v62, 16, v117
	v_and_b32_e32 v63, 0xffff0000, v117
	v_pk_mul_f32 v[62:63], v[62:63], v[44:45]
	v_pk_fma_f32 v[62:63], v[62:63], v[4:5], v[166:167]
	v_cvt_pk_bf16_f32 v117, v62, v63
	v_lshlrev_b32_e32 v64, 16, v118
	v_and_b32_e32 v65, 0xffff0000, v118
	v_pk_mul_f32 v[64:65], v[64:65], v[44:45]
	v_pk_fma_f32 v[64:65], v[64:65], v[6:7], v[168:169]
	v_cvt_pk_bf16_f32 v118, v64, v65
	v_lshlrev_b32_e32 v66, 16, v119
	v_and_b32_e32 v67, 0xffff0000, v119
	v_pk_mul_f32 v[66:67], v[66:67], v[44:45]
	v_pk_fma_f32 v[66:67], v[66:67], v[8:9], v[170:171]
	v_cvt_pk_bf16_f32 v119, v66, v67
	v_lshlrev_b32_e32 v60, 16, v120
	v_and_b32_e32 v61, 0xffff0000, v120
	v_pk_mul_f32 v[60:61], v[60:61], v[44:45]
	v_pk_fma_f32 v[60:61], v[60:61], v[10:11], v[172:173]
	v_cvt_pk_bf16_f32 v120, v60, v61
	v_lshlrev_b32_e32 v62, 16, v121
	v_and_b32_e32 v63, 0xffff0000, v121
	v_pk_mul_f32 v[62:63], v[62:63], v[44:45]
	v_pk_fma_f32 v[62:63], v[62:63], v[12:13], v[174:175]
	v_cvt_pk_bf16_f32 v121, v62, v63
	v_lshlrev_b32_e32 v64, 16, v122
	v_and_b32_e32 v65, 0xffff0000, v122
	v_pk_mul_f32 v[64:65], v[64:65], v[44:45]
	v_pk_fma_f32 v[64:65], v[64:65], v[14:15], v[176:177]
	v_cvt_pk_bf16_f32 v122, v64, v65
	v_lshlrev_b32_e32 v66, 16, v123
	v_and_b32_e32 v67, 0xffff0000, v123
	v_pk_mul_f32 v[66:67], v[66:67], v[44:45]
	v_pk_fma_f32 v[66:67], v[66:67], v[16:17], v[178:179]
	v_cvt_pk_bf16_f32 v123, v66, v67
	v_lshlrev_b32_e32 v60, 16, v124
	v_and_b32_e32 v61, 0xffff0000, v124
	v_pk_mul_f32 v[60:61], v[60:61], v[44:45]
	v_pk_fma_f32 v[60:61], v[60:61], v[18:19], v[180:181]
	v_cvt_pk_bf16_f32 v124, v60, v61
	v_lshlrev_b32_e32 v62, 16, v125
	v_and_b32_e32 v63, 0xffff0000, v125
	v_pk_mul_f32 v[62:63], v[62:63], v[44:45]
	v_pk_fma_f32 v[62:63], v[62:63], v[20:21], v[182:183]
	v_cvt_pk_bf16_f32 v125, v62, v63
	v_lshlrev_b32_e32 v64, 16, v126
	v_and_b32_e32 v65, 0xffff0000, v126
	v_pk_mul_f32 v[64:65], v[64:65], v[44:45]
	v_pk_fma_f32 v[64:65], v[64:65], v[22:23], v[184:185]
	v_cvt_pk_bf16_f32 v126, v64, v65
	v_lshlrev_b32_e32 v66, 16, v127
	v_and_b32_e32 v67, 0xffff0000, v127
	v_pk_mul_f32 v[66:67], v[66:67], v[44:45]
	v_pk_fma_f32 v[66:67], v[66:67], v[24:25], v[186:187]
	v_cvt_pk_bf16_f32 v127, v66, v67
	v_lshlrev_b32_e32 v60, 16, v128
	v_and_b32_e32 v61, 0xffff0000, v128
	v_pk_mul_f32 v[60:61], v[60:61], v[44:45]
	v_pk_fma_f32 v[60:61], v[60:61], v[26:27], v[188:189]
	v_cvt_pk_bf16_f32 v128, v60, v61
	v_lshlrev_b32_e32 v62, 16, v129
	v_and_b32_e32 v63, 0xffff0000, v129
	v_pk_mul_f32 v[62:63], v[62:63], v[44:45]
	v_pk_fma_f32 v[62:63], v[62:63], v[28:29], v[190:191]
	v_cvt_pk_bf16_f32 v129, v62, v63
	v_lshlrev_b32_e32 v64, 16, v130
	v_and_b32_e32 v65, 0xffff0000, v130
	v_pk_mul_f32 v[64:65], v[64:65], v[44:45]
	v_pk_fma_f32 v[64:65], v[64:65], v[30:31], v[192:193]
	v_cvt_pk_bf16_f32 v130, v64, v65
	v_lshlrev_b32_e32 v66, 16, v131
	v_and_b32_e32 v67, 0xffff0000, v131
	v_pk_mul_f32 v[66:67], v[66:67], v[44:45]
	v_pk_fma_f32 v[66:67], v[66:67], v[32:33], v[194:195]
	v_cvt_pk_bf16_f32 v131, v66, v67
	global_store_dwordx4 v39, v[116:119], s[20:21]
	global_store_dwordx4 v39, v[120:123], s[20:21] offset:1024
	global_store_dwordx4 v39, v[124:127], s[20:21] offset:2048
	global_store_dwordx4 v39, v[128:131], s[20:21] offset:3072
	s_add_u32 s20, s20, 0x1000
	s_addc_u32 s21, s21, 0
	global_load_dwordx4 v[116:119], v39, s[10:11]
	global_load_dwordx4 v[120:123], v39, s[10:11] offset:1024
	global_load_dwordx4 v[124:127], v39, s[10:11] offset:2048
	global_load_dwordx4 v[128:131], v39, s[10:11] offset:3072
	s_add_u32 s10, s10, 0x1000
	s_addc_u32 s11, s11, 0
	s_waitcnt vmcnt(20)
	v_lshlrev_b32_e32 v60, 16, v132
	v_and_b32_e32 v61, 0xffff0000, v132
	v_pk_mul_f32 v[42:43], v[60:61], v[60:61]
	v_lshlrev_b32_e32 v62, 16, v133
	v_and_b32_e32 v63, 0xffff0000, v133
	v_pk_fma_f32 v[42:43], v[62:63], v[62:63], v[42:43]
	v_lshlrev_b32_e32 v64, 16, v134
	v_and_b32_e32 v65, 0xffff0000, v134
	v_pk_fma_f32 v[42:43], v[64:65], v[64:65], v[42:43]
	v_lshlrev_b32_e32 v66, 16, v135
	v_and_b32_e32 v67, 0xffff0000, v135
	v_pk_fma_f32 v[42:43], v[66:67], v[66:67], v[42:43]
	v_lshlrev_b32_e32 v60, 16, v136
	v_and_b32_e32 v61, 0xffff0000, v136
	v_pk_fma_f32 v[42:43], v[60:61], v[60:61], v[42:43]
	v_lshlrev_b32_e32 v62, 16, v137
	v_and_b32_e32 v63, 0xffff0000, v137
	v_pk_fma_f32 v[42:43], v[62:63], v[62:63], v[42:43]
	v_lshlrev_b32_e32 v64, 16, v138
	v_and_b32_e32 v65, 0xffff0000, v138
	v_pk_fma_f32 v[42:43], v[64:65], v[64:65], v[42:43]
	v_lshlrev_b32_e32 v66, 16, v139
	v_and_b32_e32 v67, 0xffff0000, v139
	v_pk_fma_f32 v[42:43], v[66:67], v[66:67], v[42:43]
	v_lshlrev_b32_e32 v60, 16, v140
	v_and_b32_e32 v61, 0xffff0000, v140
	v_pk_fma_f32 v[42:43], v[60:61], v[60:61], v[42:43]
	v_lshlrev_b32_e32 v62, 16, v141
	v_and_b32_e32 v63, 0xffff0000, v141
	v_pk_fma_f32 v[42:43], v[62:63], v[62:63], v[42:43]
	v_lshlrev_b32_e32 v64, 16, v142
	v_and_b32_e32 v65, 0xffff0000, v142
	v_pk_fma_f32 v[42:43], v[64:65], v[64:65], v[42:43]
	v_lshlrev_b32_e32 v66, 16, v143
	v_and_b32_e32 v67, 0xffff0000, v143
	v_pk_fma_f32 v[42:43], v[66:67], v[66:67], v[42:43]
	v_lshlrev_b32_e32 v60, 16, v144
	v_and_b32_e32 v61, 0xffff0000, v144
	v_pk_fma_f32 v[42:43], v[60:61], v[60:61], v[42:43]
	v_lshlrev_b32_e32 v62, 16, v145
	v_and_b32_e32 v63, 0xffff0000, v145
	v_pk_fma_f32 v[42:43], v[62:63], v[62:63], v[42:43]
	v_lshlrev_b32_e32 v64, 16, v146
	v_and_b32_e32 v65, 0xffff0000, v146
	v_pk_fma_f32 v[42:43], v[64:65], v[64:65], v[42:43]
	v_lshlrev_b32_e32 v66, 16, v147
	v_and_b32_e32 v67, 0xffff0000, v147
	v_pk_fma_f32 v[42:43], v[66:67], v[66:67], v[42:43]
	v_add_f32_e32 v42, v42, v43
	s_nop 1
	v_add_f32_dpp v42, v42, v42 quad_perm:[1,0,3,2] row_mask:0xf bank_mask:0xf
	s_nop 1
	v_add_f32_dpp v42, v42, v42 quad_perm:[2,3,0,1] row_mask:0xf bank_mask:0xf
	s_nop 1
	v_add_f32_dpp v42, v42, v42 row_half_mirror row_mask:0xf bank_mask:0xf
	s_nop 1
	v_add_f32_dpp v42, v42, v42 row_mirror row_mask:0xf bank_mask:0xf
	s_nop 1
	v_add_f32_dpp v42, v42, v42 row_bcast:15 row_mask:0xa bank_mask:0xf
	s_nop 1
	v_add_f32_dpp v42, v42, v42 row_bcast:31 row_mask:0xc bank_mask:0xf
	s_nop 1
	v_readlane_b32 s100, v42, 63
	s_nop 3
	v_mov_b32_e32 v44, s100
	v_fma_f32 v44, v44, v47, v224
	v_rsq_f32_e32 v45, v44
	s_nop 0
	v_mul_f32_e32 v46, v44, v45
	v_mul_f32_e32 v46, v46, v45
	v_fmaak_f32 v46, -0.5, v46, 0x3fc00000
	v_mul_f32_e32 v44, v45, v46
	v_mov_b32_e32 v45, v44
	v_lshlrev_b32_e32 v60, 16, v132
	v_and_b32_e32 v61, 0xffff0000, v132
	v_pk_mul_f32 v[60:61], v[60:61], v[44:45]
	v_pk_fma_f32 v[60:61], v[60:61], v[2:3], v[164:165]
	v_cvt_pk_bf16_f32 v132, v60, v61
	v_lshlrev_b32_e32 v62, 16, v133
	v_and_b32_e32 v63, 0xffff0000, v133
	v_pk_mul_f32 v[62:63], v[62:63], v[44:45]
	v_pk_fma_f32 v[62:63], v[62:63], v[4:5], v[166:167]
	v_cvt_pk_bf16_f32 v133, v62, v63
	v_lshlrev_b32_e32 v64, 16, v134
	v_and_b32_e32 v65, 0xffff0000, v134
	v_pk_mul_f32 v[64:65], v[64:65], v[44:45]
	v_pk_fma_f32 v[64:65], v[64:65], v[6:7], v[168:169]
	v_cvt_pk_bf16_f32 v134, v64, v65
	v_lshlrev_b32_e32 v66, 16, v135
	v_and_b32_e32 v67, 0xffff0000, v135
	v_pk_mul_f32 v[66:67], v[66:67], v[44:45]
	v_pk_fma_f32 v[66:67], v[66:67], v[8:9], v[170:171]
	v_cvt_pk_bf16_f32 v135, v66, v67
	v_lshlrev_b32_e32 v60, 16, v136
	v_and_b32_e32 v61, 0xffff0000, v136
	v_pk_mul_f32 v[60:61], v[60:61], v[44:45]
	v_pk_fma_f32 v[60:61], v[60:61], v[10:11], v[172:173]
	v_cvt_pk_bf16_f32 v136, v60, v61
	v_lshlrev_b32_e32 v62, 16, v137
	v_and_b32_e32 v63, 0xffff0000, v137
	v_pk_mul_f32 v[62:63], v[62:63], v[44:45]
	v_pk_fma_f32 v[62:63], v[62:63], v[12:13], v[174:175]
	v_cvt_pk_bf16_f32 v137, v62, v63
	v_lshlrev_b32_e32 v64, 16, v138
	v_and_b32_e32 v65, 0xffff0000, v138
	v_pk_mul_f32 v[64:65], v[64:65], v[44:45]
	v_pk_fma_f32 v[64:65], v[64:65], v[14:15], v[176:177]
	v_cvt_pk_bf16_f32 v138, v64, v65
	v_lshlrev_b32_e32 v66, 16, v139
	v_and_b32_e32 v67, 0xffff0000, v139
	v_pk_mul_f32 v[66:67], v[66:67], v[44:45]
	v_pk_fma_f32 v[66:67], v[66:67], v[16:17], v[178:179]
	v_cvt_pk_bf16_f32 v139, v66, v67
	v_lshlrev_b32_e32 v60, 16, v140
	v_and_b32_e32 v61, 0xffff0000, v140
	v_pk_mul_f32 v[60:61], v[60:61], v[44:45]
	v_pk_fma_f32 v[60:61], v[60:61], v[18:19], v[180:181]
	v_cvt_pk_bf16_f32 v140, v60, v61
	v_lshlrev_b32_e32 v62, 16, v141
	v_and_b32_e32 v63, 0xffff0000, v141
	v_pk_mul_f32 v[62:63], v[62:63], v[44:45]
	v_pk_fma_f32 v[62:63], v[62:63], v[20:21], v[182:183]
	v_cvt_pk_bf16_f32 v141, v62, v63
	v_lshlrev_b32_e32 v64, 16, v142
	v_and_b32_e32 v65, 0xffff0000, v142
	v_pk_mul_f32 v[64:65], v[64:65], v[44:45]
	v_pk_fma_f32 v[64:65], v[64:65], v[22:23], v[184:185]
	v_cvt_pk_bf16_f32 v142, v64, v65
	v_lshlrev_b32_e32 v66, 16, v143
	v_and_b32_e32 v67, 0xffff0000, v143
	v_pk_mul_f32 v[66:67], v[66:67], v[44:45]
	v_pk_fma_f32 v[66:67], v[66:67], v[24:25], v[186:187]
	v_cvt_pk_bf16_f32 v143, v66, v67
	v_lshlrev_b32_e32 v60, 16, v144
	v_and_b32_e32 v61, 0xffff0000, v144
	v_pk_mul_f32 v[60:61], v[60:61], v[44:45]
	v_pk_fma_f32 v[60:61], v[60:61], v[26:27], v[188:189]
	v_cvt_pk_bf16_f32 v144, v60, v61
	v_lshlrev_b32_e32 v62, 16, v145
	v_and_b32_e32 v63, 0xffff0000, v145
	v_pk_mul_f32 v[62:63], v[62:63], v[44:45]
	v_pk_fma_f32 v[62:63], v[62:63], v[28:29], v[190:191]
	v_cvt_pk_bf16_f32 v145, v62, v63
	v_lshlrev_b32_e32 v64, 16, v146
	v_and_b32_e32 v65, 0xffff0000, v146
	v_pk_mul_f32 v[64:65], v[64:65], v[44:45]
	v_pk_fma_f32 v[64:65], v[64:65], v[30:31], v[192:193]
	v_cvt_pk_bf16_f32 v146, v64, v65
	v_lshlrev_b32_e32 v66, 16, v147
	v_and_b32_e32 v67, 0xffff0000, v147
	v_pk_mul_f32 v[66:67], v[66:67], v[44:45]
	v_pk_fma_f32 v[66:67], v[66:67], v[32:33], v[194:195]
	v_cvt_pk_bf16_f32 v147, v66, v67
	global_store_dwordx4 v39, v[132:135], s[20:21]
	global_store_dwordx4 v39, v[136:139], s[20:21] offset:1024
	global_store_dwordx4 v39, v[140:143], s[20:21] offset:2048
	global_store_dwordx4 v39, v[144:147], s[20:21] offset:3072
	s_add_u32 s20, s20, 0x1000
	s_addc_u32 s21, s21, 0
	global_load_dwordx4 v[132:135], v39, s[10:11]
	global_load_dwordx4 v[136:139], v39, s[10:11] offset:1024
	global_load_dwordx4 v[140:143], v39, s[10:11] offset:2048
	global_load_dwordx4 v[144:147], v39, s[10:11] offset:3072
	s_add_u32 s10, s10, 0x1000
	s_addc_u32 s11, s11, 0
	s_waitcnt vmcnt(24)
	v_lshlrev_b32_e32 v60, 16, v148
	v_and_b32_e32 v61, 0xffff0000, v148
	v_pk_mul_f32 v[42:43], v[60:61], v[60:61]
	v_lshlrev_b32_e32 v62, 16, v149
	v_and_b32_e32 v63, 0xffff0000, v149
	v_pk_fma_f32 v[42:43], v[62:63], v[62:63], v[42:43]
	v_lshlrev_b32_e32 v64, 16, v150
	v_and_b32_e32 v65, 0xffff0000, v150
	v_pk_fma_f32 v[42:43], v[64:65], v[64:65], v[42:43]
	v_lshlrev_b32_e32 v66, 16, v151
	v_and_b32_e32 v67, 0xffff0000, v151
	v_pk_fma_f32 v[42:43], v[66:67], v[66:67], v[42:43]
	v_lshlrev_b32_e32 v60, 16, v152
	v_and_b32_e32 v61, 0xffff0000, v152
	v_pk_fma_f32 v[42:43], v[60:61], v[60:61], v[42:43]
	v_lshlrev_b32_e32 v62, 16, v153
	v_and_b32_e32 v63, 0xffff0000, v153
	v_pk_fma_f32 v[42:43], v[62:63], v[62:63], v[42:43]
	v_lshlrev_b32_e32 v64, 16, v154
	v_and_b32_e32 v65, 0xffff0000, v154
	v_pk_fma_f32 v[42:43], v[64:65], v[64:65], v[42:43]
	v_lshlrev_b32_e32 v66, 16, v155
	v_and_b32_e32 v67, 0xffff0000, v155
	v_pk_fma_f32 v[42:43], v[66:67], v[66:67], v[42:43]
	v_lshlrev_b32_e32 v60, 16, v156
	v_and_b32_e32 v61, 0xffff0000, v156
	v_pk_fma_f32 v[42:43], v[60:61], v[60:61], v[42:43]
	v_lshlrev_b32_e32 v62, 16, v157
	v_and_b32_e32 v63, 0xffff0000, v157
	v_pk_fma_f32 v[42:43], v[62:63], v[62:63], v[42:43]
	v_lshlrev_b32_e32 v64, 16, v158
	v_and_b32_e32 v65, 0xffff0000, v158
	v_pk_fma_f32 v[42:43], v[64:65], v[64:65], v[42:43]
	v_lshlrev_b32_e32 v66, 16, v159
	v_and_b32_e32 v67, 0xffff0000, v159
	v_pk_fma_f32 v[42:43], v[66:67], v[66:67], v[42:43]
	v_lshlrev_b32_e32 v60, 16, v160
	v_and_b32_e32 v61, 0xffff0000, v160
	v_pk_fma_f32 v[42:43], v[60:61], v[60:61], v[42:43]
	v_lshlrev_b32_e32 v62, 16, v161
	v_and_b32_e32 v63, 0xffff0000, v161
	v_pk_fma_f32 v[42:43], v[62:63], v[62:63], v[42:43]
	v_lshlrev_b32_e32 v64, 16, v162
	v_and_b32_e32 v65, 0xffff0000, v162
	v_pk_fma_f32 v[42:43], v[64:65], v[64:65], v[42:43]
	v_lshlrev_b32_e32 v66, 16, v163
	v_and_b32_e32 v67, 0xffff0000, v163
	v_pk_fma_f32 v[42:43], v[66:67], v[66:67], v[42:43]
	v_add_f32_e32 v42, v42, v43
	s_nop 1
	v_add_f32_dpp v42, v42, v42 quad_perm:[1,0,3,2] row_mask:0xf bank_mask:0xf
	s_nop 1
	v_add_f32_dpp v42, v42, v42 quad_perm:[2,3,0,1] row_mask:0xf bank_mask:0xf
	s_nop 1
	v_add_f32_dpp v42, v42, v42 row_half_mirror row_mask:0xf bank_mask:0xf
	s_nop 1
	v_add_f32_dpp v42, v42, v42 row_mirror row_mask:0xf bank_mask:0xf
	s_nop 1
	v_add_f32_dpp v42, v42, v42 row_bcast:15 row_mask:0xa bank_mask:0xf
	s_nop 1
	v_add_f32_dpp v42, v42, v42 row_bcast:31 row_mask:0xc bank_mask:0xf
	s_nop 1
	v_readlane_b32 s100, v42, 63
	s_nop 3
	v_mov_b32_e32 v44, s100
	v_fma_f32 v44, v44, v47, v224
	v_rsq_f32_e32 v45, v44
	s_nop 0
	v_mul_f32_e32 v46, v44, v45
	v_mul_f32_e32 v46, v46, v45
	v_fmaak_f32 v46, -0.5, v46, 0x3fc00000
	v_mul_f32_e32 v44, v45, v46
	v_mov_b32_e32 v45, v44
	v_lshlrev_b32_e32 v60, 16, v148
	v_and_b32_e32 v61, 0xffff0000, v148
	v_pk_mul_f32 v[60:61], v[60:61], v[44:45]
	v_pk_fma_f32 v[60:61], v[60:61], v[2:3], v[164:165]
	v_cvt_pk_bf16_f32 v148, v60, v61
	v_lshlrev_b32_e32 v62, 16, v149
	v_and_b32_e32 v63, 0xffff0000, v149
	v_pk_mul_f32 v[62:63], v[62:63], v[44:45]
	v_pk_fma_f32 v[62:63], v[62:63], v[4:5], v[166:167]
	v_cvt_pk_bf16_f32 v149, v62, v63
	v_lshlrev_b32_e32 v64, 16, v150
	v_and_b32_e32 v65, 0xffff0000, v150
	v_pk_mul_f32 v[64:65], v[64:65], v[44:45]
	v_pk_fma_f32 v[64:65], v[64:65], v[6:7], v[168:169]
	v_cvt_pk_bf16_f32 v150, v64, v65
	v_lshlrev_b32_e32 v66, 16, v151
	v_and_b32_e32 v67, 0xffff0000, v151
	v_pk_mul_f32 v[66:67], v[66:67], v[44:45]
	v_pk_fma_f32 v[66:67], v[66:67], v[8:9], v[170:171]
	v_cvt_pk_bf16_f32 v151, v66, v67
	v_lshlrev_b32_e32 v60, 16, v152
	v_and_b32_e32 v61, 0xffff0000, v152
	v_pk_mul_f32 v[60:61], v[60:61], v[44:45]
	v_pk_fma_f32 v[60:61], v[60:61], v[10:11], v[172:173]
	v_cvt_pk_bf16_f32 v152, v60, v61
	v_lshlrev_b32_e32 v62, 16, v153
	v_and_b32_e32 v63, 0xffff0000, v153
	v_pk_mul_f32 v[62:63], v[62:63], v[44:45]
	v_pk_fma_f32 v[62:63], v[62:63], v[12:13], v[174:175]
	v_cvt_pk_bf16_f32 v153, v62, v63
	v_lshlrev_b32_e32 v64, 16, v154
	v_and_b32_e32 v65, 0xffff0000, v154
	v_pk_mul_f32 v[64:65], v[64:65], v[44:45]
	v_pk_fma_f32 v[64:65], v[64:65], v[14:15], v[176:177]
	v_cvt_pk_bf16_f32 v154, v64, v65
	v_lshlrev_b32_e32 v66, 16, v155
	v_and_b32_e32 v67, 0xffff0000, v155
	v_pk_mul_f32 v[66:67], v[66:67], v[44:45]
	v_pk_fma_f32 v[66:67], v[66:67], v[16:17], v[178:179]
	v_cvt_pk_bf16_f32 v155, v66, v67
	v_lshlrev_b32_e32 v60, 16, v156
	v_and_b32_e32 v61, 0xffff0000, v156
	v_pk_mul_f32 v[60:61], v[60:61], v[44:45]
	v_pk_fma_f32 v[60:61], v[60:61], v[18:19], v[180:181]
	v_cvt_pk_bf16_f32 v156, v60, v61
	v_lshlrev_b32_e32 v62, 16, v157
	v_and_b32_e32 v63, 0xffff0000, v157
	v_pk_mul_f32 v[62:63], v[62:63], v[44:45]
	v_pk_fma_f32 v[62:63], v[62:63], v[20:21], v[182:183]
	v_cvt_pk_bf16_f32 v157, v62, v63
	v_lshlrev_b32_e32 v64, 16, v158
	v_and_b32_e32 v65, 0xffff0000, v158
	v_pk_mul_f32 v[64:65], v[64:65], v[44:45]
	v_pk_fma_f32 v[64:65], v[64:65], v[22:23], v[184:185]
	v_cvt_pk_bf16_f32 v158, v64, v65
	v_lshlrev_b32_e32 v66, 16, v159
	v_and_b32_e32 v67, 0xffff0000, v159
	v_pk_mul_f32 v[66:67], v[66:67], v[44:45]
	v_pk_fma_f32 v[66:67], v[66:67], v[24:25], v[186:187]
	v_cvt_pk_bf16_f32 v159, v66, v67
	v_lshlrev_b32_e32 v60, 16, v160
	v_and_b32_e32 v61, 0xffff0000, v160
	v_pk_mul_f32 v[60:61], v[60:61], v[44:45]
	v_pk_fma_f32 v[60:61], v[60:61], v[26:27], v[188:189]
	v_cvt_pk_bf16_f32 v160, v60, v61
	v_lshlrev_b32_e32 v62, 16, v161
	v_and_b32_e32 v63, 0xffff0000, v161
	v_pk_mul_f32 v[62:63], v[62:63], v[44:45]
	v_pk_fma_f32 v[62:63], v[62:63], v[28:29], v[190:191]
	v_cvt_pk_bf16_f32 v161, v62, v63
	v_lshlrev_b32_e32 v64, 16, v162
	v_and_b32_e32 v65, 0xffff0000, v162
	v_pk_mul_f32 v[64:65], v[64:65], v[44:45]
	v_pk_fma_f32 v[64:65], v[64:65], v[30:31], v[192:193]
	v_cvt_pk_bf16_f32 v162, v64, v65
	v_lshlrev_b32_e32 v66, 16, v163
	v_and_b32_e32 v67, 0xffff0000, v163
	v_pk_mul_f32 v[66:67], v[66:67], v[44:45]
	v_pk_fma_f32 v[66:67], v[66:67], v[32:33], v[194:195]
	v_cvt_pk_bf16_f32 v163, v66, v67
	global_store_dwordx4 v39, v[148:151], s[20:21]
	global_store_dwordx4 v39, v[152:155], s[20:21] offset:1024
	global_store_dwordx4 v39, v[156:159], s[20:21] offset:2048
	global_store_dwordx4 v39, v[160:163], s[20:21] offset:3072
	s_add_u32 s20, s20, 0x1000
	s_addc_u32 s21, s21, 0
	global_load_dwordx4 v[148:151], v39, s[10:11]
	global_load_dwordx4 v[152:155], v39, s[10:11] offset:1024
	global_load_dwordx4 v[156:159], v39, s[10:11] offset:2048
	global_load_dwordx4 v[160:163], v39, s[10:11] offset:3072
	s_add_u32 s10, s10, 0x1000
	s_addc_u32 s11, s11, 0
	s_waitcnt vmcnt(24)
	v_lshlrev_b32_e32 v60, 16, v100
	v_and_b32_e32 v61, 0xffff0000, v100
	v_pk_mul_f32 v[42:43], v[60:61], v[60:61]
	v_lshlrev_b32_e32 v62, 16, v101
	v_and_b32_e32 v63, 0xffff0000, v101
	v_pk_fma_f32 v[42:43], v[62:63], v[62:63], v[42:43]
	v_lshlrev_b32_e32 v64, 16, v102
	v_and_b32_e32 v65, 0xffff0000, v102
	v_pk_fma_f32 v[42:43], v[64:65], v[64:65], v[42:43]
	v_lshlrev_b32_e32 v66, 16, v103
	v_and_b32_e32 v67, 0xffff0000, v103
	v_pk_fma_f32 v[42:43], v[66:67], v[66:67], v[42:43]
	v_lshlrev_b32_e32 v60, 16, v104
	v_and_b32_e32 v61, 0xffff0000, v104
	v_pk_fma_f32 v[42:43], v[60:61], v[60:61], v[42:43]
	v_lshlrev_b32_e32 v62, 16, v105
	v_and_b32_e32 v63, 0xffff0000, v105
	v_pk_fma_f32 v[42:43], v[62:63], v[62:63], v[42:43]
	v_lshlrev_b32_e32 v64, 16, v106
	v_and_b32_e32 v65, 0xffff0000, v106
	v_pk_fma_f32 v[42:43], v[64:65], v[64:65], v[42:43]
	v_lshlrev_b32_e32 v66, 16, v107
	v_and_b32_e32 v67, 0xffff0000, v107
	v_pk_fma_f32 v[42:43], v[66:67], v[66:67], v[42:43]
	v_lshlrev_b32_e32 v60, 16, v108
	v_and_b32_e32 v61, 0xffff0000, v108
	v_pk_fma_f32 v[42:43], v[60:61], v[60:61], v[42:43]
	v_lshlrev_b32_e32 v62, 16, v109
	v_and_b32_e32 v63, 0xffff0000, v109
	v_pk_fma_f32 v[42:43], v[62:63], v[62:63], v[42:43]
	v_lshlrev_b32_e32 v64, 16, v110
	v_and_b32_e32 v65, 0xffff0000, v110
	v_pk_fma_f32 v[42:43], v[64:65], v[64:65], v[42:43]
	v_lshlrev_b32_e32 v66, 16, v111
	v_and_b32_e32 v67, 0xffff0000, v111
	v_pk_fma_f32 v[42:43], v[66:67], v[66:67], v[42:43]
	v_lshlrev_b32_e32 v60, 16, v112
	v_and_b32_e32 v61, 0xffff0000, v112
	v_pk_fma_f32 v[42:43], v[60:61], v[60:61], v[42:43]
	v_lshlrev_b32_e32 v62, 16, v113
	v_and_b32_e32 v63, 0xffff0000, v113
	v_pk_fma_f32 v[42:43], v[62:63], v[62:63], v[42:43]
	v_lshlrev_b32_e32 v64, 16, v114
	v_and_b32_e32 v65, 0xffff0000, v114
	v_pk_fma_f32 v[42:43], v[64:65], v[64:65], v[42:43]
	v_lshlrev_b32_e32 v66, 16, v115
	v_and_b32_e32 v67, 0xffff0000, v115
	v_pk_fma_f32 v[42:43], v[66:67], v[66:67], v[42:43]
	v_add_f32_e32 v42, v42, v43
	s_nop 1
	v_add_f32_dpp v42, v42, v42 quad_perm:[1,0,3,2] row_mask:0xf bank_mask:0xf
	s_nop 1
	v_add_f32_dpp v42, v42, v42 quad_perm:[2,3,0,1] row_mask:0xf bank_mask:0xf
	s_nop 1
	v_add_f32_dpp v42, v42, v42 row_half_mirror row_mask:0xf bank_mask:0xf
	s_nop 1
	v_add_f32_dpp v42, v42, v42 row_mirror row_mask:0xf bank_mask:0xf
	s_nop 1
	v_add_f32_dpp v42, v42, v42 row_bcast:15 row_mask:0xa bank_mask:0xf
	s_nop 1
	v_add_f32_dpp v42, v42, v42 row_bcast:31 row_mask:0xc bank_mask:0xf
	s_nop 1
	v_readlane_b32 s100, v42, 63
	s_nop 3
	v_mov_b32_e32 v44, s100
	v_fma_f32 v44, v44, v47, v224
	v_rsq_f32_e32 v45, v44
	s_nop 0
	v_mul_f32_e32 v46, v44, v45
	v_mul_f32_e32 v46, v46, v45
	v_fmaak_f32 v46, -0.5, v46, 0x3fc00000
	v_mul_f32_e32 v44, v45, v46
	v_mov_b32_e32 v45, v44
	v_lshlrev_b32_e32 v60, 16, v100
	v_and_b32_e32 v61, 0xffff0000, v100
	v_pk_mul_f32 v[60:61], v[60:61], v[44:45]
	v_pk_fma_f32 v[60:61], v[60:61], v[2:3], v[164:165]
	v_cvt_pk_bf16_f32 v100, v60, v61
	v_lshlrev_b32_e32 v62, 16, v101
	v_and_b32_e32 v63, 0xffff0000, v101
	v_pk_mul_f32 v[62:63], v[62:63], v[44:45]
	v_pk_fma_f32 v[62:63], v[62:63], v[4:5], v[166:167]
	v_cvt_pk_bf16_f32 v101, v62, v63
	v_lshlrev_b32_e32 v64, 16, v102
	v_and_b32_e32 v65, 0xffff0000, v102
	v_pk_mul_f32 v[64:65], v[64:65], v[44:45]
	v_pk_fma_f32 v[64:65], v[64:65], v[6:7], v[168:169]
	v_cvt_pk_bf16_f32 v102, v64, v65
	v_lshlrev_b32_e32 v66, 16, v103
	v_and_b32_e32 v67, 0xffff0000, v103
	v_pk_mul_f32 v[66:67], v[66:67], v[44:45]
	v_pk_fma_f32 v[66:67], v[66:67], v[8:9], v[170:171]
	v_cvt_pk_bf16_f32 v103, v66, v67
	v_lshlrev_b32_e32 v60, 16, v104
	v_and_b32_e32 v61, 0xffff0000, v104
	v_pk_mul_f32 v[60:61], v[60:61], v[44:45]
	v_pk_fma_f32 v[60:61], v[60:61], v[10:11], v[172:173]
	v_cvt_pk_bf16_f32 v104, v60, v61
	v_lshlrev_b32_e32 v62, 16, v105
	v_and_b32_e32 v63, 0xffff0000, v105
	v_pk_mul_f32 v[62:63], v[62:63], v[44:45]
	v_pk_fma_f32 v[62:63], v[62:63], v[12:13], v[174:175]
	v_cvt_pk_bf16_f32 v105, v62, v63
	v_lshlrev_b32_e32 v64, 16, v106
	v_and_b32_e32 v65, 0xffff0000, v106
	v_pk_mul_f32 v[64:65], v[64:65], v[44:45]
	v_pk_fma_f32 v[64:65], v[64:65], v[14:15], v[176:177]
	v_cvt_pk_bf16_f32 v106, v64, v65
	v_lshlrev_b32_e32 v66, 16, v107
	v_and_b32_e32 v67, 0xffff0000, v107
	v_pk_mul_f32 v[66:67], v[66:67], v[44:45]
	v_pk_fma_f32 v[66:67], v[66:67], v[16:17], v[178:179]
	v_cvt_pk_bf16_f32 v107, v66, v67
	v_lshlrev_b32_e32 v60, 16, v108
	v_and_b32_e32 v61, 0xffff0000, v108
	v_pk_mul_f32 v[60:61], v[60:61], v[44:45]
	v_pk_fma_f32 v[60:61], v[60:61], v[18:19], v[180:181]
	v_cvt_pk_bf16_f32 v108, v60, v61
	v_lshlrev_b32_e32 v62, 16, v109
	v_and_b32_e32 v63, 0xffff0000, v109
	v_pk_mul_f32 v[62:63], v[62:63], v[44:45]
	v_pk_fma_f32 v[62:63], v[62:63], v[20:21], v[182:183]
	v_cvt_pk_bf16_f32 v109, v62, v63
	v_lshlrev_b32_e32 v64, 16, v110
	v_and_b32_e32 v65, 0xffff0000, v110
	v_pk_mul_f32 v[64:65], v[64:65], v[44:45]
	v_pk_fma_f32 v[64:65], v[64:65], v[22:23], v[184:185]
	v_cvt_pk_bf16_f32 v110, v64, v65
	v_lshlrev_b32_e32 v66, 16, v111
	v_and_b32_e32 v67, 0xffff0000, v111
	v_pk_mul_f32 v[66:67], v[66:67], v[44:45]
	v_pk_fma_f32 v[66:67], v[66:67], v[24:25], v[186:187]
	v_cvt_pk_bf16_f32 v111, v66, v67
	v_lshlrev_b32_e32 v60, 16, v112
	v_and_b32_e32 v61, 0xffff0000, v112
	v_pk_mul_f32 v[60:61], v[60:61], v[44:45]
	v_pk_fma_f32 v[60:61], v[60:61], v[26:27], v[188:189]
	v_cvt_pk_bf16_f32 v112, v60, v61
	v_lshlrev_b32_e32 v62, 16, v113
	v_and_b32_e32 v63, 0xffff0000, v113
	v_pk_mul_f32 v[62:63], v[62:63], v[44:45]
	v_pk_fma_f32 v[62:63], v[62:63], v[28:29], v[190:191]
	v_cvt_pk_bf16_f32 v113, v62, v63
	v_lshlrev_b32_e32 v64, 16, v114
	v_and_b32_e32 v65, 0xffff0000, v114
	v_pk_mul_f32 v[64:65], v[64:65], v[44:45]
	v_pk_fma_f32 v[64:65], v[64:65], v[30:31], v[192:193]
	v_cvt_pk_bf16_f32 v114, v64, v65
	v_lshlrev_b32_e32 v66, 16, v115
	v_and_b32_e32 v67, 0xffff0000, v115
	v_pk_mul_f32 v[66:67], v[66:67], v[44:45]
	v_pk_fma_f32 v[66:67], v[66:67], v[32:33], v[194:195]
	v_cvt_pk_bf16_f32 v115, v66, v67
	global_store_dwordx4 v39, v[100:103], s[20:21]
	global_store_dwordx4 v39, v[104:107], s[20:21] offset:1024
	global_store_dwordx4 v39, v[108:111], s[20:21] offset:2048
	global_store_dwordx4 v39, v[112:115], s[20:21] offset:3072
	s_add_u32 s20, s20, 0x1000
	s_addc_u32 s21, s21, 0
	s_waitcnt vmcnt(20)
	v_lshlrev_b32_e32 v60, 16, v116
	v_and_b32_e32 v61, 0xffff0000, v116
	v_pk_mul_f32 v[42:43], v[60:61], v[60:61]
	v_lshlrev_b32_e32 v62, 16, v117
	v_and_b32_e32 v63, 0xffff0000, v117
	v_pk_fma_f32 v[42:43], v[62:63], v[62:63], v[42:43]
	v_lshlrev_b32_e32 v64, 16, v118
	v_and_b32_e32 v65, 0xffff0000, v118
	v_pk_fma_f32 v[42:43], v[64:65], v[64:65], v[42:43]
	v_lshlrev_b32_e32 v66, 16, v119
	v_and_b32_e32 v67, 0xffff0000, v119
	v_pk_fma_f32 v[42:43], v[66:67], v[66:67], v[42:43]
	v_lshlrev_b32_e32 v60, 16, v120
	v_and_b32_e32 v61, 0xffff0000, v120
	v_pk_fma_f32 v[42:43], v[60:61], v[60:61], v[42:43]
	v_lshlrev_b32_e32 v62, 16, v121
	v_and_b32_e32 v63, 0xffff0000, v121
	v_pk_fma_f32 v[42:43], v[62:63], v[62:63], v[42:43]
	v_lshlrev_b32_e32 v64, 16, v122
	v_and_b32_e32 v65, 0xffff0000, v122
	v_pk_fma_f32 v[42:43], v[64:65], v[64:65], v[42:43]
	v_lshlrev_b32_e32 v66, 16, v123
	v_and_b32_e32 v67, 0xffff0000, v123
	v_pk_fma_f32 v[42:43], v[66:67], v[66:67], v[42:43]
	v_lshlrev_b32_e32 v60, 16, v124
	v_and_b32_e32 v61, 0xffff0000, v124
	v_pk_fma_f32 v[42:43], v[60:61], v[60:61], v[42:43]
	v_lshlrev_b32_e32 v62, 16, v125
	v_and_b32_e32 v63, 0xffff0000, v125
	v_pk_fma_f32 v[42:43], v[62:63], v[62:63], v[42:43]
	v_lshlrev_b32_e32 v64, 16, v126
	v_and_b32_e32 v65, 0xffff0000, v126
	v_pk_fma_f32 v[42:43], v[64:65], v[64:65], v[42:43]
	v_lshlrev_b32_e32 v66, 16, v127
	v_and_b32_e32 v67, 0xffff0000, v127
	v_pk_fma_f32 v[42:43], v[66:67], v[66:67], v[42:43]
	v_lshlrev_b32_e32 v60, 16, v128
	v_and_b32_e32 v61, 0xffff0000, v128
	v_pk_fma_f32 v[42:43], v[60:61], v[60:61], v[42:43]
	v_lshlrev_b32_e32 v62, 16, v129
	v_and_b32_e32 v63, 0xffff0000, v129
	v_pk_fma_f32 v[42:43], v[62:63], v[62:63], v[42:43]
	v_lshlrev_b32_e32 v64, 16, v130
	v_and_b32_e32 v65, 0xffff0000, v130
	v_pk_fma_f32 v[42:43], v[64:65], v[64:65], v[42:43]
	v_lshlrev_b32_e32 v66, 16, v131
	v_and_b32_e32 v67, 0xffff0000, v131
	v_pk_fma_f32 v[42:43], v[66:67], v[66:67], v[42:43]
	v_add_f32_e32 v42, v42, v43
	s_nop 1
	v_add_f32_dpp v42, v42, v42 quad_perm:[1,0,3,2] row_mask:0xf bank_mask:0xf
	s_nop 1
	v_add_f32_dpp v42, v42, v42 quad_perm:[2,3,0,1] row_mask:0xf bank_mask:0xf
	s_nop 1
	v_add_f32_dpp v42, v42, v42 row_half_mirror row_mask:0xf bank_mask:0xf
	s_nop 1
	v_add_f32_dpp v42, v42, v42 row_mirror row_mask:0xf bank_mask:0xf
	s_nop 1
	v_add_f32_dpp v42, v42, v42 row_bcast:15 row_mask:0xa bank_mask:0xf
	s_nop 1
	v_add_f32_dpp v42, v42, v42 row_bcast:31 row_mask:0xc bank_mask:0xf
	s_nop 1
	v_readlane_b32 s100, v42, 63
	s_nop 3
	v_mov_b32_e32 v44, s100
	v_fma_f32 v44, v44, v47, v224
	v_rsq_f32_e32 v45, v44
	s_nop 0
	v_mul_f32_e32 v46, v44, v45
	v_mul_f32_e32 v46, v46, v45
	v_fmaak_f32 v46, -0.5, v46, 0x3fc00000
	v_mul_f32_e32 v44, v45, v46
	v_mov_b32_e32 v45, v44
	v_lshlrev_b32_e32 v60, 16, v116
	v_and_b32_e32 v61, 0xffff0000, v116
	v_pk_mul_f32 v[60:61], v[60:61], v[44:45]
	v_pk_fma_f32 v[60:61], v[60:61], v[2:3], v[164:165]
	v_cvt_pk_bf16_f32 v116, v60, v61
	v_lshlrev_b32_e32 v62, 16, v117
	v_and_b32_e32 v63, 0xffff0000, v117
	v_pk_mul_f32 v[62:63], v[62:63], v[44:45]
	v_pk_fma_f32 v[62:63], v[62:63], v[4:5], v[166:167]
	v_cvt_pk_bf16_f32 v117, v62, v63
	v_lshlrev_b32_e32 v64, 16, v118
	v_and_b32_e32 v65, 0xffff0000, v118
	v_pk_mul_f32 v[64:65], v[64:65], v[44:45]
	v_pk_fma_f32 v[64:65], v[64:65], v[6:7], v[168:169]
	v_cvt_pk_bf16_f32 v118, v64, v65
	v_lshlrev_b32_e32 v66, 16, v119
	v_and_b32_e32 v67, 0xffff0000, v119
	v_pk_mul_f32 v[66:67], v[66:67], v[44:45]
	v_pk_fma_f32 v[66:67], v[66:67], v[8:9], v[170:171]
	v_cvt_pk_bf16_f32 v119, v66, v67
	v_lshlrev_b32_e32 v60, 16, v120
	v_and_b32_e32 v61, 0xffff0000, v120
	v_pk_mul_f32 v[60:61], v[60:61], v[44:45]
	v_pk_fma_f32 v[60:61], v[60:61], v[10:11], v[172:173]
	v_cvt_pk_bf16_f32 v120, v60, v61
	v_lshlrev_b32_e32 v62, 16, v121
	v_and_b32_e32 v63, 0xffff0000, v121
	v_pk_mul_f32 v[62:63], v[62:63], v[44:45]
	v_pk_fma_f32 v[62:63], v[62:63], v[12:13], v[174:175]
	v_cvt_pk_bf16_f32 v121, v62, v63
	v_lshlrev_b32_e32 v64, 16, v122
	v_and_b32_e32 v65, 0xffff0000, v122
	v_pk_mul_f32 v[64:65], v[64:65], v[44:45]
	v_pk_fma_f32 v[64:65], v[64:65], v[14:15], v[176:177]
	v_cvt_pk_bf16_f32 v122, v64, v65
	v_lshlrev_b32_e32 v66, 16, v123
	v_and_b32_e32 v67, 0xffff0000, v123
	v_pk_mul_f32 v[66:67], v[66:67], v[44:45]
	v_pk_fma_f32 v[66:67], v[66:67], v[16:17], v[178:179]
	v_cvt_pk_bf16_f32 v123, v66, v67
	v_lshlrev_b32_e32 v60, 16, v124
	v_and_b32_e32 v61, 0xffff0000, v124
	v_pk_mul_f32 v[60:61], v[60:61], v[44:45]
	v_pk_fma_f32 v[60:61], v[60:61], v[18:19], v[180:181]
	v_cvt_pk_bf16_f32 v124, v60, v61
	v_lshlrev_b32_e32 v62, 16, v125
	v_and_b32_e32 v63, 0xffff0000, v125
	v_pk_mul_f32 v[62:63], v[62:63], v[44:45]
	v_pk_fma_f32 v[62:63], v[62:63], v[20:21], v[182:183]
	v_cvt_pk_bf16_f32 v125, v62, v63
	v_lshlrev_b32_e32 v64, 16, v126
	v_and_b32_e32 v65, 0xffff0000, v126
	v_pk_mul_f32 v[64:65], v[64:65], v[44:45]
	v_pk_fma_f32 v[64:65], v[64:65], v[22:23], v[184:185]
	v_cvt_pk_bf16_f32 v126, v64, v65
	v_lshlrev_b32_e32 v66, 16, v127
	v_and_b32_e32 v67, 0xffff0000, v127
	v_pk_mul_f32 v[66:67], v[66:67], v[44:45]
	v_pk_fma_f32 v[66:67], v[66:67], v[24:25], v[186:187]
	v_cvt_pk_bf16_f32 v127, v66, v67
	v_lshlrev_b32_e32 v60, 16, v128
	v_and_b32_e32 v61, 0xffff0000, v128
	v_pk_mul_f32 v[60:61], v[60:61], v[44:45]
	v_pk_fma_f32 v[60:61], v[60:61], v[26:27], v[188:189]
	v_cvt_pk_bf16_f32 v128, v60, v61
	v_lshlrev_b32_e32 v62, 16, v129
	v_and_b32_e32 v63, 0xffff0000, v129
	v_pk_mul_f32 v[62:63], v[62:63], v[44:45]
	v_pk_fma_f32 v[62:63], v[62:63], v[28:29], v[190:191]
	v_cvt_pk_bf16_f32 v129, v62, v63
	v_lshlrev_b32_e32 v64, 16, v130
	v_and_b32_e32 v65, 0xffff0000, v130
	v_pk_mul_f32 v[64:65], v[64:65], v[44:45]
	v_pk_fma_f32 v[64:65], v[64:65], v[30:31], v[192:193]
	v_cvt_pk_bf16_f32 v130, v64, v65
	v_lshlrev_b32_e32 v66, 16, v131
	v_and_b32_e32 v67, 0xffff0000, v131
	v_pk_mul_f32 v[66:67], v[66:67], v[44:45]
	v_pk_fma_f32 v[66:67], v[66:67], v[32:33], v[194:195]
	v_cvt_pk_bf16_f32 v131, v66, v67
	global_store_dwordx4 v39, v[116:119], s[20:21]
	global_store_dwordx4 v39, v[120:123], s[20:21] offset:1024
	global_store_dwordx4 v39, v[124:127], s[20:21] offset:2048
	global_store_dwordx4 v39, v[128:131], s[20:21] offset:3072
	s_add_u32 s20, s20, 0x1000
	s_addc_u32 s21, s21, 0
	s_waitcnt vmcnt(16)
	v_lshlrev_b32_e32 v60, 16, v132
	v_and_b32_e32 v61, 0xffff0000, v132
	v_pk_mul_f32 v[42:43], v[60:61], v[60:61]
	v_lshlrev_b32_e32 v62, 16, v133
	v_and_b32_e32 v63, 0xffff0000, v133
	v_pk_fma_f32 v[42:43], v[62:63], v[62:63], v[42:43]
	v_lshlrev_b32_e32 v64, 16, v134
	v_and_b32_e32 v65, 0xffff0000, v134
	v_pk_fma_f32 v[42:43], v[64:65], v[64:65], v[42:43]
	v_lshlrev_b32_e32 v66, 16, v135
	v_and_b32_e32 v67, 0xffff0000, v135
	v_pk_fma_f32 v[42:43], v[66:67], v[66:67], v[42:43]
	v_lshlrev_b32_e32 v60, 16, v136
	v_and_b32_e32 v61, 0xffff0000, v136
	v_pk_fma_f32 v[42:43], v[60:61], v[60:61], v[42:43]
	v_lshlrev_b32_e32 v62, 16, v137
	v_and_b32_e32 v63, 0xffff0000, v137
	v_pk_fma_f32 v[42:43], v[62:63], v[62:63], v[42:43]
	v_lshlrev_b32_e32 v64, 16, v138
	v_and_b32_e32 v65, 0xffff0000, v138
	v_pk_fma_f32 v[42:43], v[64:65], v[64:65], v[42:43]
	v_lshlrev_b32_e32 v66, 16, v139
	v_and_b32_e32 v67, 0xffff0000, v139
	v_pk_fma_f32 v[42:43], v[66:67], v[66:67], v[42:43]
	v_lshlrev_b32_e32 v60, 16, v140
	v_and_b32_e32 v61, 0xffff0000, v140
	v_pk_fma_f32 v[42:43], v[60:61], v[60:61], v[42:43]
	v_lshlrev_b32_e32 v62, 16, v141
	v_and_b32_e32 v63, 0xffff0000, v141
	v_pk_fma_f32 v[42:43], v[62:63], v[62:63], v[42:43]
	v_lshlrev_b32_e32 v64, 16, v142
	v_and_b32_e32 v65, 0xffff0000, v142
	v_pk_fma_f32 v[42:43], v[64:65], v[64:65], v[42:43]
	v_lshlrev_b32_e32 v66, 16, v143
	v_and_b32_e32 v67, 0xffff0000, v143
	v_pk_fma_f32 v[42:43], v[66:67], v[66:67], v[42:43]
	v_lshlrev_b32_e32 v60, 16, v144
	v_and_b32_e32 v61, 0xffff0000, v144
	v_pk_fma_f32 v[42:43], v[60:61], v[60:61], v[42:43]
	v_lshlrev_b32_e32 v62, 16, v145
	v_and_b32_e32 v63, 0xffff0000, v145
	v_pk_fma_f32 v[42:43], v[62:63], v[62:63], v[42:43]
	v_lshlrev_b32_e32 v64, 16, v146
	v_and_b32_e32 v65, 0xffff0000, v146
	v_pk_fma_f32 v[42:43], v[64:65], v[64:65], v[42:43]
	v_lshlrev_b32_e32 v66, 16, v147
	v_and_b32_e32 v67, 0xffff0000, v147
	v_pk_fma_f32 v[42:43], v[66:67], v[66:67], v[42:43]
	v_add_f32_e32 v42, v42, v43
	s_nop 1
	v_add_f32_dpp v42, v42, v42 quad_perm:[1,0,3,2] row_mask:0xf bank_mask:0xf
	s_nop 1
	v_add_f32_dpp v42, v42, v42 quad_perm:[2,3,0,1] row_mask:0xf bank_mask:0xf
	s_nop 1
	v_add_f32_dpp v42, v42, v42 row_half_mirror row_mask:0xf bank_mask:0xf
	s_nop 1
	v_add_f32_dpp v42, v42, v42 row_mirror row_mask:0xf bank_mask:0xf
	s_nop 1
	v_add_f32_dpp v42, v42, v42 row_bcast:15 row_mask:0xa bank_mask:0xf
	s_nop 1
	v_add_f32_dpp v42, v42, v42 row_bcast:31 row_mask:0xc bank_mask:0xf
	s_nop 1
	v_readlane_b32 s100, v42, 63
	s_nop 3
	v_mov_b32_e32 v44, s100
	v_fma_f32 v44, v44, v47, v224
	v_rsq_f32_e32 v45, v44
	s_nop 0
	v_mul_f32_e32 v46, v44, v45
	v_mul_f32_e32 v46, v46, v45
	v_fmaak_f32 v46, -0.5, v46, 0x3fc00000
	v_mul_f32_e32 v44, v45, v46
	v_mov_b32_e32 v45, v44
	v_lshlrev_b32_e32 v60, 16, v132
	v_and_b32_e32 v61, 0xffff0000, v132
	v_pk_mul_f32 v[60:61], v[60:61], v[44:45]
	v_pk_fma_f32 v[60:61], v[60:61], v[2:3], v[164:165]
	v_cvt_pk_bf16_f32 v132, v60, v61
	v_lshlrev_b32_e32 v62, 16, v133
	v_and_b32_e32 v63, 0xffff0000, v133
	v_pk_mul_f32 v[62:63], v[62:63], v[44:45]
	v_pk_fma_f32 v[62:63], v[62:63], v[4:5], v[166:167]
	v_cvt_pk_bf16_f32 v133, v62, v63
	v_lshlrev_b32_e32 v64, 16, v134
	v_and_b32_e32 v65, 0xffff0000, v134
	v_pk_mul_f32 v[64:65], v[64:65], v[44:45]
	v_pk_fma_f32 v[64:65], v[64:65], v[6:7], v[168:169]
	v_cvt_pk_bf16_f32 v134, v64, v65
	v_lshlrev_b32_e32 v66, 16, v135
	v_and_b32_e32 v67, 0xffff0000, v135
	v_pk_mul_f32 v[66:67], v[66:67], v[44:45]
	v_pk_fma_f32 v[66:67], v[66:67], v[8:9], v[170:171]
	v_cvt_pk_bf16_f32 v135, v66, v67
	v_lshlrev_b32_e32 v60, 16, v136
	v_and_b32_e32 v61, 0xffff0000, v136
	v_pk_mul_f32 v[60:61], v[60:61], v[44:45]
	v_pk_fma_f32 v[60:61], v[60:61], v[10:11], v[172:173]
	v_cvt_pk_bf16_f32 v136, v60, v61
	v_lshlrev_b32_e32 v62, 16, v137
	v_and_b32_e32 v63, 0xffff0000, v137
	v_pk_mul_f32 v[62:63], v[62:63], v[44:45]
	v_pk_fma_f32 v[62:63], v[62:63], v[12:13], v[174:175]
	v_cvt_pk_bf16_f32 v137, v62, v63
	v_lshlrev_b32_e32 v64, 16, v138
	v_and_b32_e32 v65, 0xffff0000, v138
	v_pk_mul_f32 v[64:65], v[64:65], v[44:45]
	v_pk_fma_f32 v[64:65], v[64:65], v[14:15], v[176:177]
	v_cvt_pk_bf16_f32 v138, v64, v65
	v_lshlrev_b32_e32 v66, 16, v139
	v_and_b32_e32 v67, 0xffff0000, v139
	v_pk_mul_f32 v[66:67], v[66:67], v[44:45]
	v_pk_fma_f32 v[66:67], v[66:67], v[16:17], v[178:179]
	v_cvt_pk_bf16_f32 v139, v66, v67
	v_lshlrev_b32_e32 v60, 16, v140
	v_and_b32_e32 v61, 0xffff0000, v140
	v_pk_mul_f32 v[60:61], v[60:61], v[44:45]
	v_pk_fma_f32 v[60:61], v[60:61], v[18:19], v[180:181]
	v_cvt_pk_bf16_f32 v140, v60, v61
	v_lshlrev_b32_e32 v62, 16, v141
	v_and_b32_e32 v63, 0xffff0000, v141
	v_pk_mul_f32 v[62:63], v[62:63], v[44:45]
	v_pk_fma_f32 v[62:63], v[62:63], v[20:21], v[182:183]
	v_cvt_pk_bf16_f32 v141, v62, v63
	v_lshlrev_b32_e32 v64, 16, v142
	v_and_b32_e32 v65, 0xffff0000, v142
	v_pk_mul_f32 v[64:65], v[64:65], v[44:45]
	v_pk_fma_f32 v[64:65], v[64:65], v[22:23], v[184:185]
	v_cvt_pk_bf16_f32 v142, v64, v65
	v_lshlrev_b32_e32 v66, 16, v143
	v_and_b32_e32 v67, 0xffff0000, v143
	v_pk_mul_f32 v[66:67], v[66:67], v[44:45]
	v_pk_fma_f32 v[66:67], v[66:67], v[24:25], v[186:187]
	v_cvt_pk_bf16_f32 v143, v66, v67
	v_lshlrev_b32_e32 v60, 16, v144
	v_and_b32_e32 v61, 0xffff0000, v144
	v_pk_mul_f32 v[60:61], v[60:61], v[44:45]
	v_pk_fma_f32 v[60:61], v[60:61], v[26:27], v[188:189]
	v_cvt_pk_bf16_f32 v144, v60, v61
	v_lshlrev_b32_e32 v62, 16, v145
	v_and_b32_e32 v63, 0xffff0000, v145
	v_pk_mul_f32 v[62:63], v[62:63], v[44:45]
	v_pk_fma_f32 v[62:63], v[62:63], v[28:29], v[190:191]
	v_cvt_pk_bf16_f32 v145, v62, v63
	v_lshlrev_b32_e32 v64, 16, v146
	v_and_b32_e32 v65, 0xffff0000, v146
	v_pk_mul_f32 v[64:65], v[64:65], v[44:45]
	v_pk_fma_f32 v[64:65], v[64:65], v[30:31], v[192:193]
	v_cvt_pk_bf16_f32 v146, v64, v65
	v_lshlrev_b32_e32 v66, 16, v147
	v_and_b32_e32 v67, 0xffff0000, v147
	v_pk_mul_f32 v[66:67], v[66:67], v[44:45]
	v_pk_fma_f32 v[66:67], v[66:67], v[32:33], v[194:195]
	v_cvt_pk_bf16_f32 v147, v66, v67
	global_store_dwordx4 v39, v[132:135], s[20:21]
	global_store_dwordx4 v39, v[136:139], s[20:21] offset:1024
	global_store_dwordx4 v39, v[140:143], s[20:21] offset:2048
	global_store_dwordx4 v39, v[144:147], s[20:21] offset:3072
	s_add_u32 s20, s20, 0x1000
	s_addc_u32 s21, s21, 0
	s_waitcnt vmcnt(12)
	v_lshlrev_b32_e32 v60, 16, v148
	v_and_b32_e32 v61, 0xffff0000, v148
	v_pk_mul_f32 v[42:43], v[60:61], v[60:61]
	v_lshlrev_b32_e32 v62, 16, v149
	v_and_b32_e32 v63, 0xffff0000, v149
	v_pk_fma_f32 v[42:43], v[62:63], v[62:63], v[42:43]
	v_lshlrev_b32_e32 v64, 16, v150
	v_and_b32_e32 v65, 0xffff0000, v150
	v_pk_fma_f32 v[42:43], v[64:65], v[64:65], v[42:43]
	v_lshlrev_b32_e32 v66, 16, v151
	v_and_b32_e32 v67, 0xffff0000, v151
	v_pk_fma_f32 v[42:43], v[66:67], v[66:67], v[42:43]
	v_lshlrev_b32_e32 v60, 16, v152
	v_and_b32_e32 v61, 0xffff0000, v152
	v_pk_fma_f32 v[42:43], v[60:61], v[60:61], v[42:43]
	v_lshlrev_b32_e32 v62, 16, v153
	v_and_b32_e32 v63, 0xffff0000, v153
	v_pk_fma_f32 v[42:43], v[62:63], v[62:63], v[42:43]
	v_lshlrev_b32_e32 v64, 16, v154
	v_and_b32_e32 v65, 0xffff0000, v154
	v_pk_fma_f32 v[42:43], v[64:65], v[64:65], v[42:43]
	v_lshlrev_b32_e32 v66, 16, v155
	v_and_b32_e32 v67, 0xffff0000, v155
	v_pk_fma_f32 v[42:43], v[66:67], v[66:67], v[42:43]
	v_lshlrev_b32_e32 v60, 16, v156
	v_and_b32_e32 v61, 0xffff0000, v156
	v_pk_fma_f32 v[42:43], v[60:61], v[60:61], v[42:43]
	v_lshlrev_b32_e32 v62, 16, v157
	v_and_b32_e32 v63, 0xffff0000, v157
	v_pk_fma_f32 v[42:43], v[62:63], v[62:63], v[42:43]
	v_lshlrev_b32_e32 v64, 16, v158
	v_and_b32_e32 v65, 0xffff0000, v158
	v_pk_fma_f32 v[42:43], v[64:65], v[64:65], v[42:43]
	v_lshlrev_b32_e32 v66, 16, v159
	v_and_b32_e32 v67, 0xffff0000, v159
	v_pk_fma_f32 v[42:43], v[66:67], v[66:67], v[42:43]
	v_lshlrev_b32_e32 v60, 16, v160
	v_and_b32_e32 v61, 0xffff0000, v160
	v_pk_fma_f32 v[42:43], v[60:61], v[60:61], v[42:43]
	v_lshlrev_b32_e32 v62, 16, v161
	v_and_b32_e32 v63, 0xffff0000, v161
	v_pk_fma_f32 v[42:43], v[62:63], v[62:63], v[42:43]
	v_lshlrev_b32_e32 v64, 16, v162
	v_and_b32_e32 v65, 0xffff0000, v162
	v_pk_fma_f32 v[42:43], v[64:65], v[64:65], v[42:43]
	v_lshlrev_b32_e32 v66, 16, v163
	v_and_b32_e32 v67, 0xffff0000, v163
	v_pk_fma_f32 v[42:43], v[66:67], v[66:67], v[42:43]
	v_add_f32_e32 v42, v42, v43
	s_nop 1
	v_add_f32_dpp v42, v42, v42 quad_perm:[1,0,3,2] row_mask:0xf bank_mask:0xf
	s_nop 1
	v_add_f32_dpp v42, v42, v42 quad_perm:[2,3,0,1] row_mask:0xf bank_mask:0xf
	s_nop 1
	v_add_f32_dpp v42, v42, v42 row_half_mirror row_mask:0xf bank_mask:0xf
	s_nop 1
	v_add_f32_dpp v42, v42, v42 row_mirror row_mask:0xf bank_mask:0xf
	s_nop 1
	v_add_f32_dpp v42, v42, v42 row_bcast:15 row_mask:0xa bank_mask:0xf
	s_nop 1
	v_add_f32_dpp v42, v42, v42 row_bcast:31 row_mask:0xc bank_mask:0xf
	s_nop 1
	v_readlane_b32 s100, v42, 63
	s_nop 3
	v_mov_b32_e32 v44, s100
	v_fma_f32 v44, v44, v47, v224
	v_rsq_f32_e32 v45, v44
	s_nop 0
	v_mul_f32_e32 v46, v44, v45
	v_mul_f32_e32 v46, v46, v45
	v_fmaak_f32 v46, -0.5, v46, 0x3fc00000
	v_mul_f32_e32 v44, v45, v46
	v_mov_b32_e32 v45, v44
	v_lshlrev_b32_e32 v60, 16, v148
	v_and_b32_e32 v61, 0xffff0000, v148
	v_pk_mul_f32 v[60:61], v[60:61], v[44:45]
	v_pk_fma_f32 v[60:61], v[60:61], v[2:3], v[164:165]
	v_cvt_pk_bf16_f32 v148, v60, v61
	v_lshlrev_b32_e32 v62, 16, v149
	v_and_b32_e32 v63, 0xffff0000, v149
	v_pk_mul_f32 v[62:63], v[62:63], v[44:45]
	v_pk_fma_f32 v[62:63], v[62:63], v[4:5], v[166:167]
	v_cvt_pk_bf16_f32 v149, v62, v63
	v_lshlrev_b32_e32 v64, 16, v150
	v_and_b32_e32 v65, 0xffff0000, v150
	v_pk_mul_f32 v[64:65], v[64:65], v[44:45]
	v_pk_fma_f32 v[64:65], v[64:65], v[6:7], v[168:169]
	v_cvt_pk_bf16_f32 v150, v64, v65
	v_lshlrev_b32_e32 v66, 16, v151
	v_and_b32_e32 v67, 0xffff0000, v151
	v_pk_mul_f32 v[66:67], v[66:67], v[44:45]
	v_pk_fma_f32 v[66:67], v[66:67], v[8:9], v[170:171]
	v_cvt_pk_bf16_f32 v151, v66, v67
	v_lshlrev_b32_e32 v60, 16, v152
	v_and_b32_e32 v61, 0xffff0000, v152
	v_pk_mul_f32 v[60:61], v[60:61], v[44:45]
	v_pk_fma_f32 v[60:61], v[60:61], v[10:11], v[172:173]
	v_cvt_pk_bf16_f32 v152, v60, v61
	v_lshlrev_b32_e32 v62, 16, v153
	v_and_b32_e32 v63, 0xffff0000, v153
	v_pk_mul_f32 v[62:63], v[62:63], v[44:45]
	v_pk_fma_f32 v[62:63], v[62:63], v[12:13], v[174:175]
	v_cvt_pk_bf16_f32 v153, v62, v63
	v_lshlrev_b32_e32 v64, 16, v154
	v_and_b32_e32 v65, 0xffff0000, v154
	v_pk_mul_f32 v[64:65], v[64:65], v[44:45]
	v_pk_fma_f32 v[64:65], v[64:65], v[14:15], v[176:177]
	v_cvt_pk_bf16_f32 v154, v64, v65
	v_lshlrev_b32_e32 v66, 16, v155
	v_and_b32_e32 v67, 0xffff0000, v155
	v_pk_mul_f32 v[66:67], v[66:67], v[44:45]
	v_pk_fma_f32 v[66:67], v[66:67], v[16:17], v[178:179]
	v_cvt_pk_bf16_f32 v155, v66, v67
	v_lshlrev_b32_e32 v60, 16, v156
	v_and_b32_e32 v61, 0xffff0000, v156
	v_pk_mul_f32 v[60:61], v[60:61], v[44:45]
	v_pk_fma_f32 v[60:61], v[60:61], v[18:19], v[180:181]
	v_cvt_pk_bf16_f32 v156, v60, v61
	v_lshlrev_b32_e32 v62, 16, v157
	v_and_b32_e32 v63, 0xffff0000, v157
	v_pk_mul_f32 v[62:63], v[62:63], v[44:45]
	v_pk_fma_f32 v[62:63], v[62:63], v[20:21], v[182:183]
	v_cvt_pk_bf16_f32 v157, v62, v63
	v_lshlrev_b32_e32 v64, 16, v158
	v_and_b32_e32 v65, 0xffff0000, v158
	v_pk_mul_f32 v[64:65], v[64:65], v[44:45]
	v_pk_fma_f32 v[64:65], v[64:65], v[22:23], v[184:185]
	v_cvt_pk_bf16_f32 v158, v64, v65
	v_lshlrev_b32_e32 v66, 16, v159
	v_and_b32_e32 v67, 0xffff0000, v159
	v_pk_mul_f32 v[66:67], v[66:67], v[44:45]
	v_pk_fma_f32 v[66:67], v[66:67], v[24:25], v[186:187]
	v_cvt_pk_bf16_f32 v159, v66, v67
	v_lshlrev_b32_e32 v60, 16, v160
	v_and_b32_e32 v61, 0xffff0000, v160
	v_pk_mul_f32 v[60:61], v[60:61], v[44:45]
	v_pk_fma_f32 v[60:61], v[60:61], v[26:27], v[188:189]
	v_cvt_pk_bf16_f32 v160, v60, v61
	v_lshlrev_b32_e32 v62, 16, v161
	v_and_b32_e32 v63, 0xffff0000, v161
	v_pk_mul_f32 v[62:63], v[62:63], v[44:45]
	v_pk_fma_f32 v[62:63], v[62:63], v[28:29], v[190:191]
	v_cvt_pk_bf16_f32 v161, v62, v63
	v_lshlrev_b32_e32 v64, 16, v162
	v_and_b32_e32 v65, 0xffff0000, v162
	v_pk_mul_f32 v[64:65], v[64:65], v[44:45]
	v_pk_fma_f32 v[64:65], v[64:65], v[30:31], v[192:193]
	v_cvt_pk_bf16_f32 v162, v64, v65
	v_lshlrev_b32_e32 v66, 16, v163
	v_and_b32_e32 v67, 0xffff0000, v163
	v_pk_mul_f32 v[66:67], v[66:67], v[44:45]
	v_pk_fma_f32 v[66:67], v[66:67], v[32:33], v[194:195]
	v_cvt_pk_bf16_f32 v163, v66, v67
	global_store_dwordx4 v39, v[148:151], s[20:21]
	global_store_dwordx4 v39, v[152:155], s[20:21] offset:1024
	global_store_dwordx4 v39, v[156:159], s[20:21] offset:2048
	global_store_dwordx4 v39, v[160:163], s[20:21] offset:3072
	s_add_u32 s20, s20, 0x1000
	s_addc_u32 s21, s21, 0
